# baseline (speedup 1.0000x reference)
; __device__ __forceinline__ int tidx() { int t = threadIdx.x; asm volatile("" : "+v"(t)); return t; }
; __device__ __forceinline__ void gemm_mainloop256(const bh* __restrict__ A, long lda, const bh* __restrict__ B, long ldb, int K,
;                                                  char* lds, f32x4 (&acc)[8][4]) {
;   constexpr int T_BYTES = 256 * 128, STAGE = 2 * T_BYTES;
;   const int tid = tidx(), lane = tid & 63, wid = tid >> 6, wr = wid >> 2, wc = wid & 3, fr = lane & 15, fq = lane >> 4;
;   const int srow = tid >> 3, sch = tid & 7;
;   const bh* Ap = A + (long)srow * lda + sch * 8;
;   const bh* Bp = B + (long)srow * ldb + sch * 8;
;   const int swo = srow * 128 + ((sch ^ (srow & 7)) << 4);
;   bf16x8 ra[4], rb[4];
;   const int nk = K >> 6;
; #pragma unroll
;   for (int i = 0; i < 4; ++i) { ra[i] = *reinterpret_cast<const bf16x8*>(Ap + (long)(64 * i) * lda); rb[i] = *reinterpret_cast<const bf16x8*>(Bp + (long)(64 * i) * ldb); }
; #pragma unroll
;   for (int i = 0; i < 4; ++i) { *reinterpret_cast<bf16x8*>(lds + swo + i * 8192) = ra[i]; *reinterpret_cast<bf16x8*>(lds + T_BYTES + swo + i * 8192) = rb[i]; }
;   __syncthreads();
; template <int OMODE>
; __device__ __forceinline__ void gemm_phase256(const bh* __restrict__ A, long lda, const bh* __restrict__ Bt, long ldb, int M, int ncols, int K,
;                                               void* Cp, long ldc, char* lds) {
;   const int tm_n = M >> 8, tn_n = ncols >> 8;
;   const int tid = tidx(), lane = tid & 63, wid = tid >> 6, wr = wid >> 2, wc = wid & 3, fr = lane & 15, fq = lane >> 4;
;   for (int tile = blockIdx.x; tile < tm_n * tn_n; tile += gridDim.x) {
;     const int tn = tile / tm_n, tm = tile - tn * tm_n;
;     f32x4 acc[8][4];
; #pragma unroll
;     for (int m = 0; m < 8; ++m)
; #pragma unroll
;       for (int n = 0; n < 4; ++n) acc[m][n] = f32x4{0.f, 0.f, 0.f, 0.f};
;     gemm_mainloop256(A + (long)tm * 256 * lda, lda, Bt + (long)tn * 256 * ldb, ldb, K, lds, acc);
.LBB0_196:
	s_ashr_i32 s1, s0, 31
	s_lshl_b64 s[8:9], s[0:1], 19
	s_lshr_b32 s1, s1, 26
	s_add_i32 s1, s0, s1
	s_and_b32 s6, s1, 0xffffffc0
	s_sub_i32 s4, s0, s6
	s_ashr_i32 s5, s4, 31
	s_ashr_i32 s2, s1, 6
	s_lshl_b64 s[10:11], s[4:5], 19
	s_add_u32 s10, s38, s10
	v_mov_b32_e32 v10, v188
	s_addc_u32 s11, s39, s11
	s_ashr_i32 s3, s2, 31
	s_lshl_b64 s[12:13], s[2:3], 19
	v_ashrrev_i32_e32 v0, 3, v10
	v_readlane_b32 s14, v253, 55
	v_ashrrev_i32_e32 v1, 31, v0
	v_readlane_b32 s15, v253, 56
	s_add_u32 s12, s14, s12
	v_lshlrev_b64 v[2:3], 11, v[0:1]
	v_lshlrev_b32_e32 v1, 4, v10
	s_addc_u32 s13, s15, s13
	v_lshl_add_u64 v[4:5], s[10:11], 0, v[2:3]
	v_and_b32_e32 v176, 0x70, v1
	v_lshl_add_u64 v[4:5], v[4:5], 0, v[176:177]
	v_lshl_add_u64 v[6:7], s[12:13], 0, v[2:3]
	s_mov_b32 s1, 0x20000
	v_lshl_add_u64 v[160:161], v[6:7], 0, v[176:177]
	v_add_co_u32_e32 v6, vcc, s1, v4
	global_load_dwordx4 v[128:131], v[4:5], off
	global_load_dwordx4 v[144:147], v[160:161], off
	v_addc_co_u32_e32 v7, vcc, 0, v5, vcc
	v_add_co_u32_e32 v8, vcc, s1, v160
	s_mov_b32 s1, 0x40000
	s_nop 0
	v_addc_co_u32_e32 v9, vcc, 0, v161, vcc
	global_load_dwordx4 v[132:135], v[6:7], off
	global_load_dwordx4 v[148:151], v[8:9], off
	v_add_co_u32_e32 v6, vcc, s1, v4
	v_lshrrev_b32_e32 v1, 4, v10
	s_nop 0
	v_addc_co_u32_e32 v7, vcc, 0, v5, vcc
	v_add_co_u32_e32 v8, vcc, s1, v160
	s_mov_b32 s1, 0x60000
	s_nop 0
	v_addc_co_u32_e32 v9, vcc, 0, v161, vcc
	v_add_co_u32_e32 v4, vcc, s1, v4
	global_load_dwordx4 v[136:139], v[6:7], off
	global_load_dwordx4 v[152:155], v[8:9], off
	v_addc_co_u32_e32 v5, vcc, 0, v5, vcc
	global_load_dwordx4 v[140:143], v[4:5], off
	v_add_co_u32_e32 v4, vcc, s1, v160
	v_lshrrev_b32_e32 v6, 1, v10
	s_nop 0
	v_addc_co_u32_e32 v5, vcc, 0, v161, vcc
	global_load_dwordx4 v[156:159], v[4:5], off
	v_and_b32_e32 v4, 15, v10
	v_and_b32_e32 v8, 7, v10
	v_xor_b32_e32 v9, v0, v10
	s_mov_b32 s1, 0x1ffff80
	v_lshlrev_b32_e32 v0, 7, v0
	v_and_or_b32 v4, v6, s1, v4
	v_bitop3_b32 v1, v1, v8, 3 bitop3:0x6c
	v_lshlrev_b32_e32 v6, 4, v9
	s_movk_i32 s1, 0x70
	v_lshlrev_b32_e32 v167, 7, v4
	v_lshlrev_b32_e32 v168, 4, v1
	v_and_or_b32 v4, v6, s1, v0
	v_lshl_add_u64 v[0:1], s[8:9], 0, v[2:3]
	s_ashr_i32 s7, s6, 31
	v_lshl_or_b32 v0, v8, 4, v0
	s_lshl_b64 s[6:7], s[6:7], 19
	v_mov_b32_e32 v2, s7
	v_subrev_co_u32_e32 v0, vcc, s6, v0
	v_bfe_u32 v5, v10, 4, 2
	s_nop 0
	v_subb_co_u32_e32 v1, vcc, v1, v2, vcc
	v_lshlrev_b32_e32 v7, 7, v10
	v_bitop3_b32 v5, v5, v8, 4 bitop3:0x36
	v_lshl_add_u64 v[162:163], s[28:29], 0, v[0:1]
	v_mov_b32_e32 v0, 0
	s_mov_b32 s3, 0
	v_and_b32_e32 v166, 0x6780, v7
	v_lshlrev_b32_e32 v169, 4, v5
	v_add_u32_e32 v170, 32, v4
	s_mov_b64 s[6:7], 0
	s_mov_b32 s1, 0
	v_lshl_add_u64 v[104:105], v[162:163], 0, s[6:7]
	v_add_co_u32_e32 v64, vcc, 0x5770000, v104
	v_lshl_add_u64 v[106:107], v[160:161], 0, s[6:7]
	s_nop 0
	v_addc_co_u32_e32 v65, vcc, 0, v105, vcc
	v_add_co_u32_e32 v76, vcc, 0x5790000, v104
	global_load_dwordx4 v[64:67], v[64:65], off offset:128
	s_nop 0
	global_load_dwordx4 v[68:71], v[106:107], off offset:128
	v_addc_co_u32_e32 v77, vcc, 0, v105, vcc
	v_add_co_u32_e32 v80, vcc, 0x20000, v106
	s_nop 1
	v_addc_co_u32_e32 v81, vcc, 0, v107, vcc
	v_add_co_u32_e32 v92, vcc, 0x57b0000, v104
	global_load_dwordx4 v[76:79], v[76:77], off offset:128
	s_nop 0
	global_load_dwordx4 v[80:83], v[80:81], off offset:128
	v_addc_co_u32_e32 v93, vcc, 0, v105, vcc
	v_add_co_u32_e32 v96, vcc, 0x40000, v106
	s_nop 1
	v_addc_co_u32_e32 v97, vcc, 0, v107, vcc
	v_add_co_u32_e32 v104, vcc, 0x57d0000, v104
	global_load_dwordx4 v[92:95], v[92:93], off offset:128
	s_nop 0
	global_load_dwordx4 v[96:99], v[96:97], off offset:128
	v_addc_co_u32_e32 v105, vcc, 0, v105, vcc
	v_add_co_u32_e32 v108, vcc, 0x60000, v106
	s_nop 1
	v_addc_co_u32_e32 v109, vcc, 0, v107, vcc
	global_load_dwordx4 v[104:107], v[104:105], off offset:128
	s_nop 0
	global_load_dwordx4 v[108:111], v[108:109], off offset:128
	v_mov_b32_e32 v1, v0
	v_mov_b32_e32 v2, v0
	v_mov_b32_e32 v3, v0
	v_mov_b32_e32 v4, v0
	v_mov_b32_e32 v5, v0
	v_mov_b32_e32 v6, v0
	v_mov_b32_e32 v7, v0
	v_mov_b32_e32 v8, v0
	v_mov_b32_e32 v9, v0
	v_mov_b32_e32 v10, v0
	v_mov_b32_e32 v11, v0
	v_mov_b32_e32 v12, v0
	v_mov_b32_e32 v13, v0
	v_mov_b32_e32 v14, v0
	v_mov_b32_e32 v15, v0
	s_waitcnt vmcnt(26)
; __device__ __forceinline__ void gemm_mainloop256(const bh* __restrict__ A, long lda, const bh* __restrict__ B, long ldb, int K,
;                                                  char* lds, f32x4 (&acc)[8][4]) {
;     ...
; #pragma unroll
;   for (int i = 0; i < 4; ++i) { ra[i] = *reinterpret_cast<const bf16x8*>(Ap + (long)(64 * i) * lda); rb[i] = *reinterpret_cast<const bf16x8*>(Bp + (long)(64 * i) * ldb); }
; #pragma unroll
;   for (int i = 0; i < 4; ++i) { *reinterpret_cast<bf16x8*>(lds + swo + i * 8192) = ra[i]; *reinterpret_cast<bf16x8*>(lds + T_BYTES + swo + i * 8192) = rb[i]; }
;   __syncthreads();
; template <int OMODE>
; __device__ __forceinline__ void gemm_phase256(const bh* __restrict__ A, long lda, const bh* __restrict__ Bt, long ldb, int M, int ncols, int K,
;                                               void* Cp, long ldc, char* lds) {
;     ...
; #pragma unroll
;     for (int m = 0; m < 8; ++m)
; #pragma unroll
;       for (int n = 0; n < 4; ++n) acc[m][n] = f32x4{0.f, 0.f, 0.f, 0.f};
	v_mov_b32_e32 v16, v0
	v_mov_b32_e32 v17, v0
	v_mov_b32_e32 v18, v0
	v_mov_b32_e32 v19, v0
	v_mov_b32_e32 v20, v0
	v_mov_b32_e32 v21, v0
	v_mov_b32_e32 v22, v0
	v_mov_b32_e32 v23, v0
	s_waitcnt vmcnt(25)
	v_mov_b32_e32 v24, v0
	v_mov_b32_e32 v25, v0
	v_mov_b32_e32 v26, v0
	v_mov_b32_e32 v27, v0
	v_mov_b32_e32 v28, v0
	v_mov_b32_e32 v29, v0
	v_mov_b32_e32 v30, v0
	v_mov_b32_e32 v31, v0
	s_waitcnt vmcnt(24)
	v_mov_b32_e32 v32, v0
	v_mov_b32_e32 v33, v0
	v_mov_b32_e32 v34, v0
	v_mov_b32_e32 v35, v0
	v_mov_b32_e32 v36, v0
	v_mov_b32_e32 v37, v0
	v_mov_b32_e32 v38, v0
	v_mov_b32_e32 v39, v0
	v_mov_b32_e32 v40, v0
	v_mov_b32_e32 v41, v0
	v_mov_b32_e32 v42, v0
	v_mov_b32_e32 v43, v0
	v_mov_b32_e32 v44, v0
	v_mov_b32_e32 v45, v0
	v_mov_b32_e32 v46, v0
	v_mov_b32_e32 v47, v0
	v_mov_b32_e32 v48, v0
	v_mov_b32_e32 v49, v0
	v_mov_b32_e32 v50, v0
	v_mov_b32_e32 v51, v0
	v_mov_b32_e32 v52, v0
	v_mov_b32_e32 v53, v0
	v_mov_b32_e32 v54, v0
	v_mov_b32_e32 v55, v0
	v_mov_b32_e32 v56, v0
	v_mov_b32_e32 v57, v0
	v_mov_b32_e32 v58, v0
	v_mov_b32_e32 v59, v0
	v_mov_b32_e32 v60, v0
	v_mov_b32_e32 v61, v0
	v_mov_b32_e32 v62, v0
	v_mov_b32_e32 v63, v0
	v_mov_b32_e32 v72, v0
	v_mov_b32_e32 v73, v0
	v_mov_b32_e32 v74, v0
	v_mov_b32_e32 v75, v0
	v_mov_b32_e32 v84, v0
	v_mov_b32_e32 v85, v0
	v_mov_b32_e32 v86, v0
	v_mov_b32_e32 v87, v0
	v_mov_b32_e32 v88, v0
	v_mov_b32_e32 v89, v0
	v_mov_b32_e32 v90, v0
	v_mov_b32_e32 v91, v0
	v_mov_b32_e32 v100, v0
	v_mov_b32_e32 v101, v0
	v_mov_b32_e32 v102, v0
	v_mov_b32_e32 v103, v0
	v_mov_b32_e32 v112, v0
	v_mov_b32_e32 v113, v0
	v_mov_b32_e32 v114, v0
	v_mov_b32_e32 v115, v0
	v_mov_b32_e32 v116, v0
	v_mov_b32_e32 v117, v0
	v_mov_b32_e32 v118, v0
	v_mov_b32_e32 v119, v0
	v_mov_b32_e32 v120, v0
	v_mov_b32_e32 v121, v0
	v_mov_b32_e32 v122, v0
	v_mov_b32_e32 v123, v0
	v_mov_b32_e32 v124, v0
	v_mov_b32_e32 v125, v0
	v_mov_b32_e32 v126, v0
	v_mov_b32_e32 v127, v0
	s_waitcnt vmcnt(15)
	ds_write_b128 v170, v[128:131]
	s_waitcnt vmcnt(13)
	ds_write_b128 v170, v[132:135] offset:8192
	s_waitcnt vmcnt(11)
	ds_write_b128 v170, v[136:139] offset:16384
	s_waitcnt vmcnt(9)
	ds_write_b128 v170, v[140:143] offset:24576
	ds_write_b128 v170, v[144:147] offset:32768
	ds_write_b128 v170, v[148:151] offset:40960
	ds_write_b128 v170, v[152:155] offset:49152
	s_waitcnt vmcnt(8)
	ds_write_b128 v170, v[156:159] offset:57344
	v_mov_b32_e32 v128, v0
	v_mov_b32_e32 v129, v0
	v_mov_b32_e32 v130, v0
	v_mov_b32_e32 v131, v0
	v_mov_b32_e32 v132, v0
	v_mov_b32_e32 v133, v0
	v_mov_b32_e32 v134, v0
	v_mov_b32_e32 v135, v0
	v_mov_b32_e32 v136, v0
	v_mov_b32_e32 v137, v0
	v_mov_b32_e32 v138, v0
	v_mov_b32_e32 v139, v0
	v_mov_b32_e32 v140, v0
	v_mov_b32_e32 v141, v0
	v_mov_b32_e32 v142, v0
	v_mov_b32_e32 v143, v0
	v_mov_b32_e32 v144, v0
	v_mov_b32_e32 v145, v0
	v_mov_b32_e32 v146, v0
	v_mov_b32_e32 v147, v0
	v_mov_b32_e32 v148, v0
	v_mov_b32_e32 v149, v0
	v_mov_b32_e32 v150, v0
	v_mov_b32_e32 v151, v0
	v_mov_b32_e32 v152, v0
	v_mov_b32_e32 v153, v0
	v_mov_b32_e32 v154, v0
	v_mov_b32_e32 v155, v0
	v_mov_b32_e32 v156, v0
	v_mov_b32_e32 v157, v0
	v_mov_b32_e32 v158, v0
	v_mov_b32_e32 v159, v0
	s_waitcnt lgkmcnt(0)
	s_barrier
	s_branch .LBB0_198

; __device__ __forceinline__ int tidx() { int t = threadIdx.x; asm volatile("" : "+v"(t)); return t; }
; __device__ __forceinline__ void gemm_mainloop256(const bh* __restrict__ A, long lda, const bh* __restrict__ B, long ldb, int K,
;                                                  char* lds, f32x4 (&acc)[8][4]) {
;   constexpr int T_BYTES = 256 * 128, STAGE = 2 * T_BYTES;
;   const int tid = tidx(), lane = tid & 63, wid = tid >> 6, wr = wid >> 2, wc = wid & 3, fr = lane & 15, fq = lane >> 4;
;   const int srow = tid >> 3, sch = tid & 7;
;   const bh* Ap = A + (long)srow * lda + sch * 8;
;   const bh* Bp = B + (long)srow * ldb + sch * 8;
;   const int swo = srow * 128 + ((sch ^ (srow & 7)) << 4);
;   bf16x8 ra[4], rb[4];
;   const int nk = K >> 6;
; #pragma unroll
;   for (int i = 0; i < 4; ++i) { ra[i] = *reinterpret_cast<const bf16x8*>(Ap + (long)(64 * i) * lda); rb[i] = *reinterpret_cast<const bf16x8*>(Bp + (long)(64 * i) * ldb); }
; #pragma unroll
;   for (int i = 0; i < 4; ++i) { *reinterpret_cast<bf16x8*>(lds + swo + i * 8192) = ra[i]; *reinterpret_cast<bf16x8*>(lds + T_BYTES + swo + i * 8192) = rb[i]; }
;   __syncthreads();
; template <int OMODE>
; __device__ __forceinline__ void gemm_phase256(const bh* __restrict__ A, long lda, const bh* __restrict__ Bt, long ldb, int M, int ncols, int K,
;                                               void* Cp, long ldc, char* lds) {
;   const int tm_n = M >> 8, tn_n = ncols >> 8;
;   const int tid = tidx(), lane = tid & 63, wid = tid >> 6, wr = wid >> 2, wc = wid & 3, fr = lane & 15, fq = lane >> 4;
;   for (int tile = blockIdx.x; tile < tm_n * tn_n; tile += gridDim.x) {
;     const int tn = tile / tm_n, tm = tile - tn * tm_n;
;     f32x4 acc[8][4];
; #pragma unroll
;     for (int m = 0; m < 8; ++m)
; #pragma unroll
;       for (int n = 0; n < 4; ++n) acc[m][n] = f32x4{0.f, 0.f, 0.f, 0.f};
;     gemm_mainloop256(A + (long)tm * 256 * lda, lda, Bt + (long)tn * 256 * ldb, ldb, K, lds, acc);
.LBB0_743:
	s_ashr_i32 s1, s0, 31
	s_lshl_b64 s[10:11], s[0:1], 19
	s_lshr_b32 s1, s1, 26
	s_add_i32 s1, s0, s1
	s_and_b32 s8, s1, 0xffffffc0
	s_sub_i32 s4, s0, s8
	s_ashr_i32 s5, s4, 31
	s_ashr_i32 s2, s1, 6
	s_lshl_b64 s[6:7], s[4:5], 19
	v_mov_b32_e32 v12, v188
	s_add_u32 s14, s38, s6
	s_addc_u32 s15, s39, s7
	v_ashrrev_i32_e32 v0, 3, v12
	s_ashr_i32 s3, s2, 31
	v_ashrrev_i32_e32 v1, 31, v0
	s_lshl_b64 s[6:7], s[2:3], 19
	v_lshlrev_b64 v[2:3], 11, v[0:1]
	v_lshlrev_b32_e32 v1, 4, v12
	s_add_u32 s16, s12, s6
	v_lshl_add_u64 v[4:5], s[14:15], 0, v[2:3]
	v_and_b32_e32 v176, 0x70, v1
	s_addc_u32 s17, s13, s7
	v_lshl_add_u64 v[4:5], v[4:5], 0, v[176:177]
	s_mov_b32 s1, 0x20000
	v_lshl_add_u64 v[6:7], s[16:17], 0, v[2:3]
	v_add_co_u32_e32 v8, vcc, s1, v4
	v_lshl_add_u64 v[6:7], v[6:7], 0, v[176:177]
	s_nop 0
	v_addc_co_u32_e32 v9, vcc, 0, v5, vcc
	v_add_co_u32_e32 v10, vcc, s1, v6
	s_mov_b32 s1, 0x40000
	s_nop 0
	v_addc_co_u32_e32 v11, vcc, 0, v7, vcc
	global_load_dwordx4 v[96:99], v[4:5], off
	global_load_dwordx4 v[112:115], v[6:7], off
	global_load_dwordx4 v[100:103], v[8:9], off
	global_load_dwordx4 v[116:119], v[10:11], off
	v_add_co_u32_e32 v8, vcc, s1, v4
	v_lshrrev_b32_e32 v1, 4, v12
	s_nop 0
	v_addc_co_u32_e32 v9, vcc, 0, v5, vcc
	v_add_co_u32_e32 v10, vcc, s1, v6
	s_mov_b32 s1, 0x60000
	s_nop 0
	v_addc_co_u32_e32 v11, vcc, 0, v7, vcc
	v_add_co_u32_e32 v4, vcc, s1, v4
	global_load_dwordx4 v[104:107], v[8:9], off
	global_load_dwordx4 v[152:155], v[10:11], off
	v_addc_co_u32_e32 v5, vcc, 0, v5, vcc
	global_load_dwordx4 v[108:111], v[4:5], off
	v_add_co_u32_e32 v4, vcc, s1, v6
	v_lshrrev_b32_e32 v6, 1, v12
	s_nop 0
	v_addc_co_u32_e32 v5, vcc, 0, v7, vcc
	global_load_dwordx4 v[156:159], v[4:5], off
	v_and_b32_e32 v4, 15, v12
	v_lshlrev_b32_e32 v7, 7, v12
	v_and_b32_e32 v8, 7, v12
	v_xor_b32_e32 v9, v0, v12
	s_mov_b32 s1, 0x1ffff80
	v_lshlrev_b32_e32 v0, 7, v0
	v_and_or_b32 v4, v6, s1, v4
	v_and_b32_e32 v166, 0x6780, v7
	v_bitop3_b32 v1, v1, v8, 3 bitop3:0x6c
	v_lshlrev_b32_e32 v7, 4, v9
	s_movk_i32 s1, 0x70
	v_lshlrev_b32_e32 v6, 4, v8
	v_lshlrev_b32_e32 v167, 7, v4
	v_lshlrev_b32_e32 v168, 4, v1
	v_and_or_b32 v4, v7, s1, v0
	v_lshl_add_u64 v[0:1], s[10:11], 0, v[2:3]
	s_ashr_i32 s9, s8, 31
	v_or_b32_e32 v0, v0, v6
	s_lshl_b64 s[8:9], s[8:9], 19
	v_add_u32_e32 v170, 32, v4
	v_mov_b32_e32 v4, s9
	v_subrev_co_u32_e32 v0, vcc, s8, v0
	v_bfe_u32 v5, v12, 4, 2
	s_nop 0
	v_subb_co_u32_e32 v1, vcc, v1, v4, vcc
	v_lshl_add_u64 v[160:161], s[28:29], 0, v[0:1]
	v_lshl_add_u64 v[0:1], s[6:7], 0, v[2:3]
	v_readlane_b32 s6, v253, 55
	v_or_b32_e32 v0, v0, v6
	v_readlane_b32 s7, v253, 56
	v_bitop3_b32 v5, v5, v8, 4 bitop3:0x36
	s_mov_b32 s3, 0
	v_lshl_add_u64 v[162:163], s[6:7], 0, v[0:1]
	v_mov_b32_e32 v0, 0
	v_lshlrev_b32_e32 v169, 4, v5
	s_mov_b64 s[6:7], 0
	s_mov_b32 s1, 0
	v_lshl_add_u64 v[144:145], v[160:161], 0, s[6:7]
	v_add_co_u32_e32 v120, vcc, 0x5770000, v144
	v_lshl_add_u64 v[146:147], v[162:163], 0, s[6:7]
	s_nop 0
	v_addc_co_u32_e32 v121, vcc, 0, v145, vcc
	v_add_co_u32_e32 v124, vcc, 0x858000, v146
	s_nop 1
	v_addc_co_u32_e32 v125, vcc, 0, v147, vcc
	v_add_co_u32_e32 v128, vcc, 0x5790000, v144
	global_load_dwordx4 v[120:123], v[120:121], off offset:128
	s_nop 0
	global_load_dwordx4 v[124:127], v[124:125], off offset:128
	v_addc_co_u32_e32 v129, vcc, 0, v145, vcc
	v_add_co_u32_e32 v132, vcc, 0x878000, v146
	s_nop 1
	v_addc_co_u32_e32 v133, vcc, 0, v147, vcc
	v_add_co_u32_e32 v136, vcc, 0x57b0000, v144
	global_load_dwordx4 v[128:131], v[128:129], off offset:128
	s_nop 0
	global_load_dwordx4 v[132:135], v[132:133], off offset:128
	v_addc_co_u32_e32 v137, vcc, 0, v145, vcc
	v_add_co_u32_e32 v140, vcc, 0x898000, v146
	s_nop 1
	v_addc_co_u32_e32 v141, vcc, 0, v147, vcc
	v_add_co_u32_e32 v144, vcc, 0x57d0000, v144
	global_load_dwordx4 v[136:139], v[136:137], off offset:128
	s_nop 0
	global_load_dwordx4 v[140:143], v[140:141], off offset:128
	v_addc_co_u32_e32 v145, vcc, 0, v145, vcc
	v_add_co_u32_e32 v148, vcc, 0x8b8000, v146
	s_nop 1
	v_addc_co_u32_e32 v149, vcc, 0, v147, vcc
	global_load_dwordx4 v[144:147], v[144:145], off offset:128
	s_nop 0
	global_load_dwordx4 v[148:151], v[148:149], off offset:128
	v_mov_b32_e32 v1, v0
	v_mov_b32_e32 v2, v0
	v_mov_b32_e32 v3, v0
	v_mov_b32_e32 v4, v0
	v_mov_b32_e32 v5, v0
	v_mov_b32_e32 v6, v0
	v_mov_b32_e32 v7, v0
	v_mov_b32_e32 v8, v0
	v_mov_b32_e32 v9, v0
	v_mov_b32_e32 v10, v0
	v_mov_b32_e32 v11, v0
	v_mov_b32_e32 v12, v0
	v_mov_b32_e32 v13, v0
	v_mov_b32_e32 v14, v0
	v_mov_b32_e32 v15, v0
	v_mov_b32_e32 v16, v0
	v_mov_b32_e32 v17, v0
	v_mov_b32_e32 v18, v0
	v_mov_b32_e32 v19, v0
	v_mov_b32_e32 v20, v0
	v_mov_b32_e32 v21, v0
	v_mov_b32_e32 v22, v0
	v_mov_b32_e32 v23, v0
	v_mov_b32_e32 v24, v0
	v_mov_b32_e32 v25, v0
	v_mov_b32_e32 v26, v0
	v_mov_b32_e32 v27, v0
	v_mov_b32_e32 v28, v0
	v_mov_b32_e32 v29, v0
	v_mov_b32_e32 v30, v0
	v_mov_b32_e32 v31, v0
	v_mov_b32_e32 v32, v0
	v_mov_b32_e32 v33, v0
	v_mov_b32_e32 v34, v0
	v_mov_b32_e32 v35, v0
	v_mov_b32_e32 v36, v0
	v_mov_b32_e32 v37, v0
	v_mov_b32_e32 v38, v0
	v_mov_b32_e32 v39, v0
	v_mov_b32_e32 v40, v0
	v_mov_b32_e32 v41, v0
	v_mov_b32_e32 v42, v0
	v_mov_b32_e32 v43, v0
	v_mov_b32_e32 v44, v0
	v_mov_b32_e32 v45, v0
	v_mov_b32_e32 v46, v0
	v_mov_b32_e32 v47, v0
	v_mov_b32_e32 v48, v0
	v_mov_b32_e32 v49, v0
	v_mov_b32_e32 v50, v0
	v_mov_b32_e32 v51, v0
	v_mov_b32_e32 v52, v0
	v_mov_b32_e32 v53, v0
	v_mov_b32_e32 v54, v0
	v_mov_b32_e32 v55, v0
	v_mov_b32_e32 v56, v0
	v_mov_b32_e32 v57, v0
	v_mov_b32_e32 v58, v0
	v_mov_b32_e32 v59, v0
	v_mov_b32_e32 v60, v0
	v_mov_b32_e32 v61, v0
	v_mov_b32_e32 v62, v0
	v_mov_b32_e32 v63, v0
	v_mov_b32_e32 v64, v0
	v_mov_b32_e32 v65, v0
	v_mov_b32_e32 v66, v0
	v_mov_b32_e32 v67, v0
	v_mov_b32_e32 v68, v0
	v_mov_b32_e32 v69, v0
	v_mov_b32_e32 v70, v0
	v_mov_b32_e32 v71, v0
	v_mov_b32_e32 v72, v0
	v_mov_b32_e32 v73, v0
	v_mov_b32_e32 v74, v0
	v_mov_b32_e32 v75, v0
	v_mov_b32_e32 v76, v0
	v_mov_b32_e32 v77, v0
	v_mov_b32_e32 v78, v0
	v_mov_b32_e32 v79, v0
	v_mov_b32_e32 v80, v0
	v_mov_b32_e32 v81, v0
	v_mov_b32_e32 v82, v0
	v_mov_b32_e32 v83, v0
	v_mov_b32_e32 v84, v0
	v_mov_b32_e32 v85, v0
	v_mov_b32_e32 v86, v0
	v_mov_b32_e32 v87, v0
	v_mov_b32_e32 v88, v0
	v_mov_b32_e32 v89, v0
	v_mov_b32_e32 v90, v0
	v_mov_b32_e32 v91, v0
	v_mov_b32_e32 v92, v0
	v_mov_b32_e32 v93, v0
	v_mov_b32_e32 v94, v0
	v_mov_b32_e32 v95, v0
	s_waitcnt vmcnt(15)
; __device__ __forceinline__ void gemm_mainloop256(const bh* __restrict__ A, long lda, const bh* __restrict__ B, long ldb, int K,
;                                                  char* lds, f32x4 (&acc)[8][4]) {
;     ...
;   for (int i = 0; i < 4; ++i) { *reinterpret_cast<bf16x8*>(lds + swo + i * 8192) = ra[i]; *reinterpret_cast<bf16x8*>(lds + T_BYTES + swo + i * 8192) = rb[i]; }
; template <int OMODE>
; __device__ __forceinline__ void gemm_phase256(const bh* __restrict__ A, long lda, const bh* __restrict__ Bt, long ldb, int M, int ncols, int K,
;                                               void* Cp, long ldc, char* lds) {
;     ...
; #pragma unroll
;     for (int m = 0; m < 8; ++m)
; #pragma unroll
;       for (int n = 0; n < 4; ++n) acc[m][n] = f32x4{0.f, 0.f, 0.f, 0.f};
	ds_write_b128 v170, v[96:99]
	s_waitcnt vmcnt(13)
	ds_write_b128 v170, v[100:103] offset:8192
	s_waitcnt vmcnt(11)
	ds_write_b128 v170, v[104:107] offset:16384
	s_waitcnt vmcnt(9)
	ds_write_b128 v170, v[108:111] offset:24576
	ds_write_b128 v170, v[112:115] offset:32768
	ds_write_b128 v170, v[116:119] offset:40960
	ds_write_b128 v170, v[152:155] offset:49152
	s_waitcnt vmcnt(8)
	ds_write_b128 v170, v[156:159] offset:57344
	v_mov_b32_e32 v96, v0
	v_mov_b32_e32 v97, v0
	v_mov_b32_e32 v98, v0
	v_mov_b32_e32 v99, v0
	v_mov_b32_e32 v100, v0
	v_mov_b32_e32 v101, v0
	v_mov_b32_e32 v102, v0
	v_mov_b32_e32 v103, v0
	v_mov_b32_e32 v104, v0
	v_mov_b32_e32 v105, v0
	v_mov_b32_e32 v106, v0
	v_mov_b32_e32 v107, v0
	v_mov_b32_e32 v108, v0
	v_mov_b32_e32 v109, v0
	v_mov_b32_e32 v110, v0
	v_mov_b32_e32 v111, v0
	v_mov_b32_e32 v112, v0
	v_mov_b32_e32 v113, v0
	v_mov_b32_e32 v114, v0
	v_mov_b32_e32 v115, v0
	v_mov_b32_e32 v116, v0
	v_mov_b32_e32 v117, v0
	v_mov_b32_e32 v118, v0
	v_mov_b32_e32 v119, v0
	v_mov_b32_e32 v152, v0
	v_mov_b32_e32 v153, v0
	v_mov_b32_e32 v154, v0
	v_mov_b32_e32 v155, v0
	v_mov_b32_e32 v156, v0
	v_mov_b32_e32 v157, v0
	v_mov_b32_e32 v158, v0
	v_mov_b32_e32 v159, v0
	s_waitcnt lgkmcnt(0)
	s_barrier
	s_branch .LBB0_745

; __device__ __forceinline__ int tidx() { int t = threadIdx.x; asm volatile("" : "+v"(t)); return t; }
; __device__ __forceinline__ void gemm_mainloop256(const bh* __restrict__ A, long lda, const bh* __restrict__ B, long ldb, int K,
;                                                  char* lds, f32x4 (&acc)[8][4]) {
;   constexpr int T_BYTES = 256 * 128, STAGE = 2 * T_BYTES;
;   const int tid = tidx(), lane = tid & 63, wid = tid >> 6, wr = wid >> 2, wc = wid & 3, fr = lane & 15, fq = lane >> 4;
;   const int srow = tid >> 3, sch = tid & 7;
;   const bh* Ap = A + (long)srow * lda + sch * 8;
;   const bh* Bp = B + (long)srow * ldb + sch * 8;
;   const int swo = srow * 128 + ((sch ^ (srow & 7)) << 4);
;   bf16x8 ra[4], rb[4];
;   const int nk = K >> 6;
; #pragma unroll
;   for (int i = 0; i < 4; ++i) { ra[i] = *reinterpret_cast<const bf16x8*>(Ap + (long)(64 * i) * lda); rb[i] = *reinterpret_cast<const bf16x8*>(Bp + (long)(64 * i) * ldb); }
; #pragma unroll
;   for (int i = 0; i < 4; ++i) { *reinterpret_cast<bf16x8*>(lds + swo + i * 8192) = ra[i]; *reinterpret_cast<bf16x8*>(lds + T_BYTES + swo + i * 8192) = rb[i]; }
;   __syncthreads();
; template <int OMODE>
; __device__ __forceinline__ void gemm_phase256(const bh* __restrict__ A, long lda, const bh* __restrict__ Bt, long ldb, int M, int ncols, int K,
;                                               void* Cp, long ldc, char* lds) {
;   const int tm_n = M >> 8, tn_n = ncols >> 8;
;   const int tid = tidx(), lane = tid & 63, wid = tid >> 6, wr = wid >> 2, wc = wid & 3, fr = lane & 15, fq = lane >> 4;
;   for (int tile = blockIdx.x; tile < tm_n * tn_n; tile += gridDim.x) {
;     const int tn = tile / tm_n, tm = tile - tn * tm_n;
;     f32x4 acc[8][4];
; #pragma unroll
;     for (int m = 0; m < 8; ++m)
; #pragma unroll
;       for (int n = 0; n < 4; ++n) acc[m][n] = f32x4{0.f, 0.f, 0.f, 0.f};
;     gemm_mainloop256(A + (long)tm * 256 * lda, lda, Bt + (long)tn * 256 * ldb, ldb, K, lds, acc);
.LBB0_843:
	s_ashr_i32 s1, s0, 31
	s_lshl_b64 s[10:11], s[0:1], 19
	s_lshr_b32 s1, s1, 26
	s_add_i32 s1, s0, s1
	s_and_b32 s8, s1, 0xffffffc0
	s_sub_i32 s4, s0, s8
	s_ashr_i32 s5, s4, 31
	s_ashr_i32 s2, s1, 6
	s_lshl_b64 s[6:7], s[4:5], 19
	v_mov_b32_e32 v12, v188
	s_add_u32 s14, s40, s6
	s_addc_u32 s15, s41, s7
	v_ashrrev_i32_e32 v0, 3, v12
	s_ashr_i32 s3, s2, 31
	v_ashrrev_i32_e32 v1, 31, v0
	s_lshl_b64 s[6:7], s[2:3], 19
	v_lshlrev_b64 v[2:3], 11, v[0:1]
	v_lshlrev_b32_e32 v1, 4, v12
	s_add_u32 s16, s12, s6
	v_lshl_add_u64 v[4:5], s[14:15], 0, v[2:3]
	v_and_b32_e32 v176, 0x70, v1
	s_addc_u32 s17, s13, s7
	v_lshl_add_u64 v[4:5], v[4:5], 0, v[176:177]
	s_mov_b32 s1, 0x20000
	v_lshl_add_u64 v[6:7], s[16:17], 0, v[2:3]
	v_add_co_u32_e32 v8, vcc, s1, v4
	v_lshl_add_u64 v[6:7], v[6:7], 0, v[176:177]
	s_nop 0
	v_addc_co_u32_e32 v9, vcc, 0, v5, vcc
	v_add_co_u32_e32 v10, vcc, s1, v6
	s_mov_b32 s1, 0x40000
	s_nop 0
	v_addc_co_u32_e32 v11, vcc, 0, v7, vcc
	global_load_dwordx4 v[128:131], v[4:5], off
	global_load_dwordx4 v[144:147], v[6:7], off
	global_load_dwordx4 v[132:135], v[8:9], off
	global_load_dwordx4 v[148:151], v[10:11], off
	v_add_co_u32_e32 v8, vcc, s1, v4
	v_lshrrev_b32_e32 v1, 4, v12
	s_nop 0
	v_addc_co_u32_e32 v9, vcc, 0, v5, vcc
	v_add_co_u32_e32 v10, vcc, s1, v6
	s_mov_b32 s1, 0x60000
	s_nop 0
	v_addc_co_u32_e32 v11, vcc, 0, v7, vcc
	v_add_co_u32_e32 v4, vcc, s1, v4
	global_load_dwordx4 v[136:139], v[8:9], off
	global_load_dwordx4 v[152:155], v[10:11], off
	v_addc_co_u32_e32 v5, vcc, 0, v5, vcc
	global_load_dwordx4 v[140:143], v[4:5], off
	v_add_co_u32_e32 v4, vcc, s1, v6
	v_lshrrev_b32_e32 v6, 1, v12
	s_nop 0
	v_addc_co_u32_e32 v5, vcc, 0, v7, vcc
	global_load_dwordx4 v[156:159], v[4:5], off
	v_and_b32_e32 v4, 15, v12
	v_lshlrev_b32_e32 v7, 7, v12
	v_and_b32_e32 v8, 7, v12
	v_xor_b32_e32 v9, v0, v12
	s_mov_b32 s1, 0x1ffff80
	v_lshlrev_b32_e32 v0, 7, v0
	v_and_or_b32 v4, v6, s1, v4
	v_and_b32_e32 v166, 0x6780, v7
	v_bitop3_b32 v1, v1, v8, 3 bitop3:0x6c
	v_lshlrev_b32_e32 v7, 4, v9
	s_movk_i32 s1, 0x70
	v_lshlrev_b32_e32 v6, 4, v8
	v_lshlrev_b32_e32 v167, 7, v4
	v_lshlrev_b32_e32 v168, 4, v1
	v_and_or_b32 v4, v7, s1, v0
	v_lshl_add_u64 v[0:1], s[10:11], 0, v[2:3]
	s_ashr_i32 s9, s8, 31
	v_or_b32_e32 v0, v0, v6
	s_lshl_b64 s[8:9], s[8:9], 19
	v_add_u32_e32 v170, 32, v4
	v_mov_b32_e32 v4, s9
	v_subrev_co_u32_e32 v0, vcc, s8, v0
	v_bfe_u32 v5, v12, 4, 2
	s_nop 0
	v_subb_co_u32_e32 v1, vcc, v1, v4, vcc
	v_lshl_add_u64 v[160:161], s[28:29], 0, v[0:1]
	v_lshl_add_u64 v[0:1], s[6:7], 0, v[2:3]
	v_readlane_b32 s6, v253, 55
	v_or_b32_e32 v0, v0, v6
	v_readlane_b32 s7, v253, 56
	v_bitop3_b32 v5, v5, v8, 4 bitop3:0x36
	s_mov_b32 s3, 0
	v_lshl_add_u64 v[162:163], s[6:7], 0, v[0:1]
	v_mov_b32_e32 v0, 0
	v_lshlrev_b32_e32 v169, 4, v5
	s_mov_b64 s[6:7], 0
	s_mov_b32 s1, 0
	v_lshl_add_u64 v[116:117], v[160:161], 0, s[6:7]
	v_add_co_u32_e32 v76, vcc, 0x13f70000, v116
	v_lshl_add_u64 v[118:119], v[162:163], 0, s[6:7]
	s_nop 0
	v_addc_co_u32_e32 v77, vcc, 0, v117, vcc
	v_add_co_u32_e32 v80, vcc, 0x1458000, v118
	s_nop 1
	v_addc_co_u32_e32 v81, vcc, 0, v119, vcc
	v_add_co_u32_e32 v88, vcc, 0x13f90000, v116
	global_load_dwordx4 v[76:79], v[76:77], off offset:128
	s_nop 0
	global_load_dwordx4 v[80:83], v[80:81], off offset:128
	v_addc_co_u32_e32 v89, vcc, 0, v117, vcc
	v_add_co_u32_e32 v92, vcc, 0x1478000, v118
	s_nop 1
	v_addc_co_u32_e32 v93, vcc, 0, v119, vcc
	v_add_co_u32_e32 v100, vcc, 0x13fb0000, v116
	global_load_dwordx4 v[88:91], v[88:89], off offset:128
	s_nop 0
	global_load_dwordx4 v[92:95], v[92:93], off offset:128
	v_addc_co_u32_e32 v101, vcc, 0, v117, vcc
	v_add_co_u32_e32 v108, vcc, 0x1498000, v118
	s_nop 1
	v_addc_co_u32_e32 v109, vcc, 0, v119, vcc
	v_add_co_u32_e32 v116, vcc, 0x13fd0000, v116
	global_load_dwordx4 v[100:103], v[100:101], off offset:128
	s_nop 0
	global_load_dwordx4 v[108:111], v[108:109], off offset:128
	v_addc_co_u32_e32 v117, vcc, 0, v117, vcc
	v_add_co_u32_e32 v120, vcc, 0x14b8000, v118
	s_nop 1
	v_addc_co_u32_e32 v121, vcc, 0, v119, vcc
	global_load_dwordx4 v[116:119], v[116:117], off offset:128
	s_nop 0
	global_load_dwordx4 v[120:123], v[120:121], off offset:128
	v_mov_b32_e32 v1, v0
	v_mov_b32_e32 v2, v0
	v_mov_b32_e32 v3, v0
	v_mov_b32_e32 v4, v0
	v_mov_b32_e32 v5, v0
	v_mov_b32_e32 v6, v0
	v_mov_b32_e32 v7, v0
	v_mov_b32_e32 v8, v0
	v_mov_b32_e32 v9, v0
	v_mov_b32_e32 v10, v0
	v_mov_b32_e32 v11, v0
	v_mov_b32_e32 v12, v0
	v_mov_b32_e32 v13, v0
	v_mov_b32_e32 v14, v0
	v_mov_b32_e32 v15, v0
	v_mov_b32_e32 v16, v0
	v_mov_b32_e32 v17, v0
	v_mov_b32_e32 v18, v0
	v_mov_b32_e32 v19, v0
	v_mov_b32_e32 v20, v0
	v_mov_b32_e32 v21, v0
	v_mov_b32_e32 v22, v0
	v_mov_b32_e32 v23, v0
	v_mov_b32_e32 v24, v0
	v_mov_b32_e32 v25, v0
	v_mov_b32_e32 v26, v0
	v_mov_b32_e32 v27, v0
	v_mov_b32_e32 v28, v0
	v_mov_b32_e32 v29, v0
	v_mov_b32_e32 v30, v0
	v_mov_b32_e32 v31, v0
	v_mov_b32_e32 v32, v0
	v_mov_b32_e32 v33, v0
	v_mov_b32_e32 v34, v0
	v_mov_b32_e32 v35, v0
	v_mov_b32_e32 v36, v0
	v_mov_b32_e32 v37, v0
	v_mov_b32_e32 v38, v0
	v_mov_b32_e32 v39, v0
	v_mov_b32_e32 v40, v0
	v_mov_b32_e32 v41, v0
	v_mov_b32_e32 v42, v0
	v_mov_b32_e32 v43, v0
	v_mov_b32_e32 v44, v0
	v_mov_b32_e32 v45, v0
	v_mov_b32_e32 v46, v0
	v_mov_b32_e32 v47, v0
	v_mov_b32_e32 v48, v0
	v_mov_b32_e32 v49, v0
	v_mov_b32_e32 v50, v0
	v_mov_b32_e32 v51, v0
	v_mov_b32_e32 v52, v0
	v_mov_b32_e32 v53, v0
	v_mov_b32_e32 v54, v0
	v_mov_b32_e32 v55, v0
	v_mov_b32_e32 v56, v0
	v_mov_b32_e32 v57, v0
	v_mov_b32_e32 v58, v0
	v_mov_b32_e32 v59, v0
	v_mov_b32_e32 v60, v0
	v_mov_b32_e32 v61, v0
	v_mov_b32_e32 v62, v0
	v_mov_b32_e32 v63, v0
	v_mov_b32_e32 v64, v0
	v_mov_b32_e32 v65, v0
	v_mov_b32_e32 v66, v0
	v_mov_b32_e32 v67, v0
	v_mov_b32_e32 v68, v0
	v_mov_b32_e32 v69, v0
	v_mov_b32_e32 v70, v0
	v_mov_b32_e32 v71, v0
	v_mov_b32_e32 v72, v0
	v_mov_b32_e32 v73, v0
	v_mov_b32_e32 v74, v0
	v_mov_b32_e32 v75, v0
	v_mov_b32_e32 v84, v0
	v_mov_b32_e32 v85, v0
	v_mov_b32_e32 v86, v0
	v_mov_b32_e32 v87, v0
	v_mov_b32_e32 v96, v0
	v_mov_b32_e32 v97, v0
	v_mov_b32_e32 v98, v0
	v_mov_b32_e32 v99, v0
	v_mov_b32_e32 v104, v0
	v_mov_b32_e32 v105, v0
	v_mov_b32_e32 v106, v0
	v_mov_b32_e32 v107, v0
	v_mov_b32_e32 v112, v0
	v_mov_b32_e32 v113, v0
	v_mov_b32_e32 v114, v0
	v_mov_b32_e32 v115, v0
	v_mov_b32_e32 v124, v0
	v_mov_b32_e32 v125, v0
	v_mov_b32_e32 v126, v0
	v_mov_b32_e32 v127, v0
	s_waitcnt vmcnt(15)
; __device__ __forceinline__ void gemm_mainloop256(const bh* __restrict__ A, long lda, const bh* __restrict__ B, long ldb, int K,
;                                                  char* lds, f32x4 (&acc)[8][4]) {
;     ...
;   for (int i = 0; i < 4; ++i) { *reinterpret_cast<bf16x8*>(lds + swo + i * 8192) = ra[i]; *reinterpret_cast<bf16x8*>(lds + T_BYTES + swo + i * 8192) = rb[i]; }
; template <int OMODE>
; __device__ __forceinline__ void gemm_phase256(const bh* __restrict__ A, long lda, const bh* __restrict__ Bt, long ldb, int M, int ncols, int K,
;                                               void* Cp, long ldc, char* lds) {
;     ...
; #pragma unroll
;     for (int m = 0; m < 8; ++m)
; #pragma unroll
;       for (int n = 0; n < 4; ++n) acc[m][n] = f32x4{0.f, 0.f, 0.f, 0.f};
	ds_write_b128 v170, v[128:131]
	s_waitcnt vmcnt(13)
	ds_write_b128 v170, v[132:135] offset:8192
	s_waitcnt vmcnt(11)
	ds_write_b128 v170, v[136:139] offset:16384
	s_waitcnt vmcnt(9)
	ds_write_b128 v170, v[140:143] offset:24576
	ds_write_b128 v170, v[144:147] offset:32768
	ds_write_b128 v170, v[148:151] offset:40960
	ds_write_b128 v170, v[152:155] offset:49152
	s_waitcnt vmcnt(8)
	ds_write_b128 v170, v[156:159] offset:57344
	v_mov_b32_e32 v128, v0
	v_mov_b32_e32 v129, v0
	v_mov_b32_e32 v130, v0
	v_mov_b32_e32 v131, v0
	v_mov_b32_e32 v132, v0
	v_mov_b32_e32 v133, v0
	v_mov_b32_e32 v134, v0
	v_mov_b32_e32 v135, v0
	v_mov_b32_e32 v136, v0
	v_mov_b32_e32 v137, v0
	v_mov_b32_e32 v138, v0
	v_mov_b32_e32 v139, v0
	v_mov_b32_e32 v140, v0
	v_mov_b32_e32 v141, v0
	v_mov_b32_e32 v142, v0
	v_mov_b32_e32 v143, v0
	v_mov_b32_e32 v144, v0
	v_mov_b32_e32 v145, v0
	v_mov_b32_e32 v146, v0
	v_mov_b32_e32 v147, v0
	v_mov_b32_e32 v148, v0
	v_mov_b32_e32 v149, v0
	v_mov_b32_e32 v150, v0
	v_mov_b32_e32 v151, v0
	v_mov_b32_e32 v152, v0
	v_mov_b32_e32 v153, v0
	v_mov_b32_e32 v154, v0
	v_mov_b32_e32 v155, v0
	v_mov_b32_e32 v156, v0
	v_mov_b32_e32 v157, v0
	v_mov_b32_e32 v158, v0
	v_mov_b32_e32 v159, v0
	s_waitcnt lgkmcnt(0)
	s_barrier
	s_branch .LBB0_845

; __device__ __forceinline__ int tidx() { int t = threadIdx.x; asm volatile("" : "+v"(t)); return t; }
; __device__ __forceinline__ void gemm_mainloop256(const bh* __restrict__ A, long lda, const bh* __restrict__ B, long ldb, int K,
;                                                  char* lds, f32x4 (&acc)[8][4]) {
;   constexpr int T_BYTES = 256 * 128, STAGE = 2 * T_BYTES;
;   const int tid = tidx(), lane = tid & 63, wid = tid >> 6, wr = wid >> 2, wc = wid & 3, fr = lane & 15, fq = lane >> 4;
;   const int srow = tid >> 3, sch = tid & 7;
;   const bh* Ap = A + (long)srow * lda + sch * 8;
;   const bh* Bp = B + (long)srow * ldb + sch * 8;
;   const int swo = srow * 128 + ((sch ^ (srow & 7)) << 4);
;   bf16x8 ra[4], rb[4];
;   const int nk = K >> 6;
; #pragma unroll
;   for (int i = 0; i < 4; ++i) { ra[i] = *reinterpret_cast<const bf16x8*>(Ap + (long)(64 * i) * lda); rb[i] = *reinterpret_cast<const bf16x8*>(Bp + (long)(64 * i) * ldb); }
; #pragma unroll
;   for (int i = 0; i < 4; ++i) { *reinterpret_cast<bf16x8*>(lds + swo + i * 8192) = ra[i]; *reinterpret_cast<bf16x8*>(lds + T_BYTES + swo + i * 8192) = rb[i]; }
;   __syncthreads();
; template <int OMODE>
; __device__ __forceinline__ void gemm_phase256(const bh* __restrict__ A, long lda, const bh* __restrict__ Bt, long ldb, int M, int ncols, int K,
;                                               void* Cp, long ldc, char* lds) {
;   const int tm_n = M >> 8, tn_n = ncols >> 8;
;   const int tid = tidx(), lane = tid & 63, wid = tid >> 6, wr = wid >> 2, wc = wid & 3, fr = lane & 15, fq = lane >> 4;
;   for (int tile = blockIdx.x; tile < tm_n * tn_n; tile += gridDim.x) {
;     const int tn = tile / tm_n, tm = tile - tn * tm_n;
;     f32x4 acc[8][4];
; #pragma unroll
;     for (int m = 0; m < 8; ++m)
; #pragma unroll
;       for (int n = 0; n < 4; ++n) acc[m][n] = f32x4{0.f, 0.f, 0.f, 0.f};
;     gemm_mainloop256(A + (long)tm * 256 * lda, lda, Bt + (long)tn * 256 * ldb, ldb, K, lds, acc);
.LBB0_1031:
	s_ashr_i32 s1, s0, 31
	s_lshl_b64 s[14:15], s[0:1], 18
	s_lshr_b32 s1, s1, 26
	s_add_i32 s1, s0, s1
	s_and_b32 s12, s1, 0xffffffc0
	s_sub_i32 s4, s0, s12
	s_ashr_i32 s5, s4, 31
	s_ashr_i32 s2, s1, 6
	s_lshl_b64 s[10:11], s[4:5], 18
	v_mov_b32_e32 v12, v188
	s_add_u32 s18, s44, s10
	s_addc_u32 s19, s45, s11
	v_ashrrev_i32_e32 v0, 3, v12
	s_ashr_i32 s3, s2, 31
	v_ashrrev_i32_e32 v1, 31, v0
	s_lshl_b64 s[10:11], s[2:3], 18
	v_lshlrev_b64 v[2:3], 10, v[0:1]
	v_lshlrev_b32_e32 v1, 4, v12
	s_add_u32 s20, s16, s10
	v_lshl_add_u64 v[4:5], s[18:19], 0, v[2:3]
	v_and_b32_e32 v176, 0x70, v1
	s_addc_u32 s21, s17, s11
	v_lshl_add_u64 v[4:5], v[4:5], 0, v[176:177]
	s_mov_b32 s1, 0x10000
	v_lshl_add_u64 v[6:7], s[20:21], 0, v[2:3]
	v_add_co_u32_e32 v8, vcc, s1, v4
	v_lshl_add_u64 v[6:7], v[6:7], 0, v[176:177]
	s_nop 0
	v_addc_co_u32_e32 v9, vcc, 0, v5, vcc
	v_add_co_u32_e32 v10, vcc, s1, v6
	s_mov_b32 s1, 0x20000
	s_nop 0
	v_addc_co_u32_e32 v11, vcc, 0, v7, vcc
	global_load_dwordx4 v[128:131], v[4:5], off
	global_load_dwordx4 v[144:147], v[6:7], off
	global_load_dwordx4 v[132:135], v[8:9], off
	global_load_dwordx4 v[148:151], v[10:11], off
	v_add_co_u32_e32 v8, vcc, s1, v4
	v_lshrrev_b32_e32 v1, 4, v12
	s_nop 0
	v_addc_co_u32_e32 v9, vcc, 0, v5, vcc
	v_add_co_u32_e32 v10, vcc, s1, v6
	s_mov_b32 s1, 0x30000
	s_nop 0
	v_addc_co_u32_e32 v11, vcc, 0, v7, vcc
	v_add_co_u32_e32 v4, vcc, s1, v4
	global_load_dwordx4 v[136:139], v[8:9], off
	global_load_dwordx4 v[152:155], v[10:11], off
	v_addc_co_u32_e32 v5, vcc, 0, v5, vcc
	global_load_dwordx4 v[140:143], v[4:5], off
	v_add_co_u32_e32 v4, vcc, s1, v6
	v_lshrrev_b32_e32 v6, 1, v12
	s_nop 0
	v_addc_co_u32_e32 v5, vcc, 0, v7, vcc
	global_load_dwordx4 v[156:159], v[4:5], off
	v_and_b32_e32 v4, 15, v12
	v_lshlrev_b32_e32 v7, 7, v12
	v_and_b32_e32 v8, 7, v12
	v_xor_b32_e32 v9, v0, v12
	s_mov_b32 s1, 0x1ffff80
	v_lshlrev_b32_e32 v0, 7, v0
	v_and_or_b32 v4, v6, s1, v4
	v_and_b32_e32 v166, 0x6780, v7
	v_bitop3_b32 v1, v1, v8, 3 bitop3:0x6c
	v_lshlrev_b32_e32 v7, 4, v9
	s_movk_i32 s1, 0x70
	v_lshlrev_b32_e32 v6, 4, v8
	v_lshlrev_b32_e32 v167, 7, v4
	v_lshlrev_b32_e32 v168, 4, v1
	v_and_or_b32 v4, v7, s1, v0
	v_lshl_add_u64 v[0:1], s[14:15], 0, v[2:3]
	s_ashr_i32 s13, s12, 31
	v_or_b32_e32 v0, v0, v6
	s_lshl_b64 s[12:13], s[12:13], 18
	v_add_u32_e32 v170, 32, v4
	v_mov_b32_e32 v4, s13
	v_subrev_co_u32_e32 v0, vcc, s12, v0
	v_bfe_u32 v5, v12, 4, 2
	s_nop 0
	v_subb_co_u32_e32 v1, vcc, v1, v4, vcc
	v_lshl_add_u64 v[160:161], s[28:29], 0, v[0:1]
	v_lshl_add_u64 v[0:1], s[10:11], 0, v[2:3]
	v_readlane_b32 s10, v253, 55
	v_or_b32_e32 v0, v0, v6
	v_readlane_b32 s11, v253, 56
	v_bitop3_b32 v5, v5, v8, 4 bitop3:0x36
	s_mov_b32 s3, 0
	v_lshl_add_u64 v[162:163], s[10:11], 0, v[0:1]
	v_mov_b32_e32 v0, 0
	v_lshlrev_b32_e32 v169, 4, v5
	s_mov_b64 s[10:11], 0
	s_mov_b32 s1, 0
	v_lshl_add_u64 v[116:117], v[160:161], 0, s[10:11]
	v_add_co_u32_e32 v76, vcc, 0x16f70000, v116
	v_lshl_add_u64 v[118:119], v[162:163], 0, s[10:11]
	s_nop 0
	v_addc_co_u32_e32 v77, vcc, 0, v117, vcc
	v_add_co_u32_e32 v80, vcc, 0x1a38000, v118
	s_nop 1
	v_addc_co_u32_e32 v81, vcc, 0, v119, vcc
	v_add_co_u32_e32 v88, vcc, 0x16f80000, v116
	global_load_dwordx4 v[76:79], v[76:77], off offset:128
	s_nop 0
	global_load_dwordx4 v[80:83], v[80:81], off offset:128
	v_addc_co_u32_e32 v89, vcc, 0, v117, vcc
	v_add_co_u32_e32 v92, vcc, 0x1a48000, v118
	s_nop 1
	v_addc_co_u32_e32 v93, vcc, 0, v119, vcc
	v_add_co_u32_e32 v100, vcc, 0x16f90000, v116
	global_load_dwordx4 v[88:91], v[88:89], off offset:128
	s_nop 0
	global_load_dwordx4 v[92:95], v[92:93], off offset:128
	v_addc_co_u32_e32 v101, vcc, 0, v117, vcc
	v_add_co_u32_e32 v108, vcc, 0x1a58000, v118
	s_nop 1
	v_addc_co_u32_e32 v109, vcc, 0, v119, vcc
	v_add_co_u32_e32 v116, vcc, 0x16fa0000, v116
	global_load_dwordx4 v[100:103], v[100:101], off offset:128
	s_nop 0
	global_load_dwordx4 v[108:111], v[108:109], off offset:128
	v_addc_co_u32_e32 v117, vcc, 0, v117, vcc
	v_add_co_u32_e32 v120, vcc, 0x1a68000, v118
	s_nop 1
	v_addc_co_u32_e32 v121, vcc, 0, v119, vcc
	global_load_dwordx4 v[116:119], v[116:117], off offset:128
	s_nop 0
	global_load_dwordx4 v[120:123], v[120:121], off offset:128
	v_mov_b32_e32 v1, v0
	v_mov_b32_e32 v2, v0
	v_mov_b32_e32 v3, v0
	v_mov_b32_e32 v4, v0
	v_mov_b32_e32 v5, v0
	v_mov_b32_e32 v6, v0
	v_mov_b32_e32 v7, v0
	v_mov_b32_e32 v8, v0
	v_mov_b32_e32 v9, v0
	v_mov_b32_e32 v10, v0
	v_mov_b32_e32 v11, v0
	v_mov_b32_e32 v12, v0
	v_mov_b32_e32 v13, v0
	v_mov_b32_e32 v14, v0
	v_mov_b32_e32 v15, v0
	v_mov_b32_e32 v16, v0
	v_mov_b32_e32 v17, v0
	v_mov_b32_e32 v18, v0
	v_mov_b32_e32 v19, v0
	v_mov_b32_e32 v20, v0
	v_mov_b32_e32 v21, v0
	v_mov_b32_e32 v22, v0
	v_mov_b32_e32 v23, v0
	v_mov_b32_e32 v24, v0
	v_mov_b32_e32 v25, v0
	v_mov_b32_e32 v26, v0
	v_mov_b32_e32 v27, v0
	v_mov_b32_e32 v28, v0
	v_mov_b32_e32 v29, v0
	v_mov_b32_e32 v30, v0
	v_mov_b32_e32 v31, v0
	v_mov_b32_e32 v32, v0
	v_mov_b32_e32 v33, v0
	v_mov_b32_e32 v34, v0
	v_mov_b32_e32 v35, v0
	s_waitcnt vmcnt(49)
; __device__ __forceinline__ void gemm_mainloop256(const bh* __restrict__ A, long lda, const bh* __restrict__ B, long ldb, int K,
;                                                  char* lds, f32x4 (&acc)[8][4]) {
;     ...
;   for (int i = 0; i < 4; ++i) { *reinterpret_cast<bf16x8*>(lds + swo + i * 8192) = ra[i]; *reinterpret_cast<bf16x8*>(lds + T_BYTES + swo + i * 8192) = rb[i]; }
; template <int OMODE>
; __device__ __forceinline__ void gemm_phase256(const bh* __restrict__ A, long lda, const bh* __restrict__ Bt, long ldb, int M, int ncols, int K,
;                                               void* Cp, long ldc, char* lds) {
;     ...
; #pragma unroll
;     for (int m = 0; m < 8; ++m)
; #pragma unroll
;       for (int n = 0; n < 4; ++n) acc[m][n] = f32x4{0.f, 0.f, 0.f, 0.f};
	v_mov_b32_e32 v36, v0
	v_mov_b32_e32 v37, v0
	v_mov_b32_e32 v38, v0
	v_mov_b32_e32 v39, v0
	s_waitcnt vmcnt(48)
	v_mov_b32_e32 v40, v0
	v_mov_b32_e32 v41, v0
	v_mov_b32_e32 v42, v0
	v_mov_b32_e32 v43, v0
	v_mov_b32_e32 v44, v0
	v_mov_b32_e32 v45, v0
	v_mov_b32_e32 v46, v0
	v_mov_b32_e32 v47, v0
	v_mov_b32_e32 v48, v0
	v_mov_b32_e32 v49, v0
	v_mov_b32_e32 v50, v0
	v_mov_b32_e32 v51, v0
	v_mov_b32_e32 v52, v0
	v_mov_b32_e32 v53, v0
	v_mov_b32_e32 v54, v0
	v_mov_b32_e32 v55, v0
	v_mov_b32_e32 v56, v0
	v_mov_b32_e32 v57, v0
	v_mov_b32_e32 v58, v0
	v_mov_b32_e32 v59, v0
	v_mov_b32_e32 v60, v0
	v_mov_b32_e32 v61, v0
	v_mov_b32_e32 v62, v0
	v_mov_b32_e32 v63, v0
	v_mov_b32_e32 v64, v0
	v_mov_b32_e32 v65, v0
	v_mov_b32_e32 v66, v0
	v_mov_b32_e32 v67, v0
	v_mov_b32_e32 v68, v0
	v_mov_b32_e32 v69, v0
	v_mov_b32_e32 v70, v0
	v_mov_b32_e32 v71, v0
	v_mov_b32_e32 v72, v0
	v_mov_b32_e32 v73, v0
	v_mov_b32_e32 v74, v0
	v_mov_b32_e32 v75, v0
	v_mov_b32_e32 v84, v0
	v_mov_b32_e32 v85, v0
	v_mov_b32_e32 v86, v0
	v_mov_b32_e32 v87, v0
	v_mov_b32_e32 v96, v0
	v_mov_b32_e32 v97, v0
	v_mov_b32_e32 v98, v0
	v_mov_b32_e32 v99, v0
	v_mov_b32_e32 v104, v0
	v_mov_b32_e32 v105, v0
	v_mov_b32_e32 v106, v0
	v_mov_b32_e32 v107, v0
	v_mov_b32_e32 v112, v0
	v_mov_b32_e32 v113, v0
	v_mov_b32_e32 v114, v0
	v_mov_b32_e32 v115, v0
	v_mov_b32_e32 v124, v0
	v_mov_b32_e32 v125, v0
	v_mov_b32_e32 v126, v0
	v_mov_b32_e32 v127, v0
	s_waitcnt vmcnt(15)
	ds_write_b128 v170, v[128:131]
	s_waitcnt vmcnt(13)
	ds_write_b128 v170, v[132:135] offset:8192
	s_waitcnt vmcnt(11)
	ds_write_b128 v170, v[136:139] offset:16384
	s_waitcnt vmcnt(9)
	ds_write_b128 v170, v[140:143] offset:24576
	ds_write_b128 v170, v[144:147] offset:32768
	ds_write_b128 v170, v[148:151] offset:40960
	ds_write_b128 v170, v[152:155] offset:49152
	s_waitcnt vmcnt(8)
	ds_write_b128 v170, v[156:159] offset:57344
	v_mov_b32_e32 v128, v0
	v_mov_b32_e32 v129, v0
	v_mov_b32_e32 v130, v0
	v_mov_b32_e32 v131, v0
	v_mov_b32_e32 v132, v0
	v_mov_b32_e32 v133, v0
	v_mov_b32_e32 v134, v0
	v_mov_b32_e32 v135, v0
	v_mov_b32_e32 v136, v0
	v_mov_b32_e32 v137, v0
	v_mov_b32_e32 v138, v0
	v_mov_b32_e32 v139, v0
	v_mov_b32_e32 v140, v0
	v_mov_b32_e32 v141, v0
	v_mov_b32_e32 v142, v0
	v_mov_b32_e32 v143, v0
	v_mov_b32_e32 v144, v0
	v_mov_b32_e32 v145, v0
	v_mov_b32_e32 v146, v0
	v_mov_b32_e32 v147, v0
	v_mov_b32_e32 v148, v0
	v_mov_b32_e32 v149, v0
	v_mov_b32_e32 v150, v0
	v_mov_b32_e32 v151, v0
	v_mov_b32_e32 v152, v0
	v_mov_b32_e32 v153, v0
	v_mov_b32_e32 v154, v0
	v_mov_b32_e32 v155, v0
	v_mov_b32_e32 v156, v0
	v_mov_b32_e32 v157, v0
	v_mov_b32_e32 v158, v0
	v_mov_b32_e32 v159, v0
	s_waitcnt lgkmcnt(0)
	s_barrier
	s_branch .LBB0_1033

; __device__ __forceinline__ int tidx() { int t = threadIdx.x; asm volatile("" : "+v"(t)); return t; }
; __device__ __forceinline__ void gemm_mainloop256(const bh* __restrict__ A, long lda, const bh* __restrict__ B, long ldb, int K,
;                                                  char* lds, f32x4 (&acc)[8][4]) {
;   constexpr int T_BYTES = 256 * 128, STAGE = 2 * T_BYTES;
;   const int tid = tidx(), lane = tid & 63, wid = tid >> 6, wr = wid >> 2, wc = wid & 3, fr = lane & 15, fq = lane >> 4;
;   const int srow = tid >> 3, sch = tid & 7;
;   const bh* Ap = A + (long)srow * lda + sch * 8;
;   const bh* Bp = B + (long)srow * ldb + sch * 8;
;   const int swo = srow * 128 + ((sch ^ (srow & 7)) << 4);
;   bf16x8 ra[4], rb[4];
;   const int nk = K >> 6;
; #pragma unroll
;   for (int i = 0; i < 4; ++i) { ra[i] = *reinterpret_cast<const bf16x8*>(Ap + (long)(64 * i) * lda); rb[i] = *reinterpret_cast<const bf16x8*>(Bp + (long)(64 * i) * ldb); }
; #pragma unroll
;   for (int i = 0; i < 4; ++i) { *reinterpret_cast<bf16x8*>(lds + swo + i * 8192) = ra[i]; *reinterpret_cast<bf16x8*>(lds + T_BYTES + swo + i * 8192) = rb[i]; }
;   __syncthreads();
; template <int OMODE>
; __device__ __forceinline__ void gemm_phase256(const bh* __restrict__ A, long lda, const bh* __restrict__ Bt, long ldb, int M, int ncols, int K,
;                                               void* Cp, long ldc, char* lds) {
;   const int tm_n = M >> 8, tn_n = ncols >> 8;
;   const int tid = tidx(), lane = tid & 63, wid = tid >> 6, wr = wid >> 2, wc = wid & 3, fr = lane & 15, fq = lane >> 4;
;   for (int tile = blockIdx.x; tile < tm_n * tn_n; tile += gridDim.x) {
;     const int tn = tile / tm_n, tm = tile - tn * tm_n;
;     f32x4 acc[8][4];
; #pragma unroll
;     for (int m = 0; m < 8; ++m)
; #pragma unroll
;       for (int n = 0; n < 4; ++n) acc[m][n] = f32x4{0.f, 0.f, 0.f, 0.f};
;     gemm_mainloop256(A + (long)tm * 256 * lda, lda, Bt + (long)tn * 256 * ldb, ldb, K, lds, acc);
.LBB0_1119:
	s_ashr_i32 s1, s0, 31
	s_lshl_b64 s[12:13], s[0:1], 19
	s_lshr_b32 s1, s1, 26
	s_add_i32 s1, s0, s1
	s_and_b32 s10, s1, 0xffffffc0
	s_sub_i32 s4, s0, s10
	s_ashr_i32 s5, s4, 31
	s_ashr_i32 s2, s1, 6
	s_lshl_b64 s[8:9], s[4:5], 19
	v_mov_b32_e32 v12, v188
	s_add_u32 s16, s38, s8
	s_addc_u32 s17, s39, s9
	v_ashrrev_i32_e32 v0, 3, v12
	s_ashr_i32 s3, s2, 31
	v_ashrrev_i32_e32 v1, 31, v0
	s_lshl_b64 s[8:9], s[2:3], 19
	v_lshlrev_b64 v[2:3], 11, v[0:1]
	v_lshlrev_b32_e32 v1, 4, v12
	s_add_u32 s18, s14, s8
	v_lshl_add_u64 v[4:5], s[16:17], 0, v[2:3]
	v_and_b32_e32 v176, 0x70, v1
	s_addc_u32 s19, s15, s9
	v_lshl_add_u64 v[4:5], v[4:5], 0, v[176:177]
	s_mov_b32 s1, 0x20000
	v_lshl_add_u64 v[6:7], s[18:19], 0, v[2:3]
	v_add_co_u32_e32 v8, vcc, s1, v4
	v_lshl_add_u64 v[6:7], v[6:7], 0, v[176:177]
	s_nop 0
	v_addc_co_u32_e32 v9, vcc, 0, v5, vcc
	v_add_co_u32_e32 v10, vcc, s1, v6
	s_mov_b32 s1, 0x40000
	s_nop 0
	v_addc_co_u32_e32 v11, vcc, 0, v7, vcc
	global_load_dwordx4 v[128:131], v[4:5], off
	global_load_dwordx4 v[144:147], v[6:7], off
	global_load_dwordx4 v[132:135], v[8:9], off
	global_load_dwordx4 v[148:151], v[10:11], off
	v_add_co_u32_e32 v8, vcc, s1, v4
	v_lshrrev_b32_e32 v1, 4, v12
	s_nop 0
	v_addc_co_u32_e32 v9, vcc, 0, v5, vcc
	v_add_co_u32_e32 v10, vcc, s1, v6
	s_mov_b32 s1, 0x60000
	s_nop 0
	v_addc_co_u32_e32 v11, vcc, 0, v7, vcc
	v_add_co_u32_e32 v4, vcc, s1, v4
	global_load_dwordx4 v[136:139], v[8:9], off
	global_load_dwordx4 v[152:155], v[10:11], off
	v_addc_co_u32_e32 v5, vcc, 0, v5, vcc
	global_load_dwordx4 v[140:143], v[4:5], off
	v_add_co_u32_e32 v4, vcc, s1, v6
	v_lshrrev_b32_e32 v6, 1, v12
	s_nop 0
	v_addc_co_u32_e32 v5, vcc, 0, v7, vcc
	global_load_dwordx4 v[156:159], v[4:5], off
	v_and_b32_e32 v4, 15, v12
	v_lshlrev_b32_e32 v7, 7, v12
	v_and_b32_e32 v8, 7, v12
	v_xor_b32_e32 v9, v0, v12
	s_mov_b32 s1, 0x1ffff80
	v_lshlrev_b32_e32 v0, 7, v0
	v_and_or_b32 v4, v6, s1, v4
	v_and_b32_e32 v166, 0x6780, v7
	v_bitop3_b32 v1, v1, v8, 3 bitop3:0x6c
	v_lshlrev_b32_e32 v7, 4, v9
	s_movk_i32 s1, 0x70
	v_lshlrev_b32_e32 v6, 4, v8
	v_lshlrev_b32_e32 v167, 7, v4
	v_lshlrev_b32_e32 v168, 4, v1
	v_and_or_b32 v4, v7, s1, v0
	v_lshl_add_u64 v[0:1], s[12:13], 0, v[2:3]
	s_ashr_i32 s11, s10, 31
	v_or_b32_e32 v0, v0, v6
	s_lshl_b64 s[10:11], s[10:11], 19
	v_add_u32_e32 v170, 32, v4
	v_mov_b32_e32 v4, s11
	v_subrev_co_u32_e32 v0, vcc, s10, v0
	v_bfe_u32 v5, v12, 4, 2
	s_nop 0
	v_subb_co_u32_e32 v1, vcc, v1, v4, vcc
	v_lshl_add_u64 v[160:161], s[28:29], 0, v[0:1]
	v_lshl_add_u64 v[0:1], s[8:9], 0, v[2:3]
	v_readlane_b32 s8, v253, 55
	v_or_b32_e32 v0, v0, v6
	v_readlane_b32 s9, v253, 56
	v_bitop3_b32 v5, v5, v8, 4 bitop3:0x36
	s_mov_b32 s3, 0
	v_lshl_add_u64 v[162:163], s[8:9], 0, v[0:1]
	v_mov_b32_e32 v0, 0
	v_lshlrev_b32_e32 v169, 4, v5
	s_mov_b64 s[8:9], 0
	s_mov_b32 s1, 0
	v_lshl_add_u64 v[104:105], v[160:161], 0, s[8:9]
	v_add_co_u32_e32 v64, vcc, 0x5770000, v104
	v_lshl_add_u64 v[106:107], v[162:163], 0, s[8:9]
	s_nop 0
	v_addc_co_u32_e32 v65, vcc, 0, v105, vcc
	v_add_co_u32_e32 v68, vcc, 0x1b38000, v106
	s_nop 1
	v_addc_co_u32_e32 v69, vcc, 0, v107, vcc
	v_add_co_u32_e32 v76, vcc, 0x5790000, v104
	global_load_dwordx4 v[64:67], v[64:65], off offset:128
	s_nop 0
	global_load_dwordx4 v[68:71], v[68:69], off offset:128
	v_addc_co_u32_e32 v77, vcc, 0, v105, vcc
	v_add_co_u32_e32 v80, vcc, 0x1b58000, v106
	s_nop 1
	v_addc_co_u32_e32 v81, vcc, 0, v107, vcc
	v_add_co_u32_e32 v92, vcc, 0x57b0000, v104
	global_load_dwordx4 v[76:79], v[76:77], off offset:128
	s_nop 0
	global_load_dwordx4 v[80:83], v[80:81], off offset:128
	v_addc_co_u32_e32 v93, vcc, 0, v105, vcc
	v_add_co_u32_e32 v96, vcc, 0x1b78000, v106
	s_nop 1
	v_addc_co_u32_e32 v97, vcc, 0, v107, vcc
	v_add_co_u32_e32 v104, vcc, 0x57d0000, v104
	global_load_dwordx4 v[92:95], v[92:93], off offset:128
	s_nop 0
	global_load_dwordx4 v[96:99], v[96:97], off offset:128
	v_addc_co_u32_e32 v105, vcc, 0, v105, vcc
	v_add_co_u32_e32 v108, vcc, 0x1b98000, v106
	s_nop 1
	v_addc_co_u32_e32 v109, vcc, 0, v107, vcc
	global_load_dwordx4 v[104:107], v[104:105], off offset:128
	s_nop 0
	global_load_dwordx4 v[108:111], v[108:109], off offset:128
	v_mov_b32_e32 v1, v0
	v_mov_b32_e32 v2, v0
	v_mov_b32_e32 v3, v0
	v_mov_b32_e32 v4, v0
	v_mov_b32_e32 v5, v0
	v_mov_b32_e32 v6, v0
	v_mov_b32_e32 v7, v0
	v_mov_b32_e32 v8, v0
	v_mov_b32_e32 v9, v0
	v_mov_b32_e32 v10, v0
	v_mov_b32_e32 v11, v0
	v_mov_b32_e32 v12, v0
	v_mov_b32_e32 v13, v0
	v_mov_b32_e32 v14, v0
	v_mov_b32_e32 v15, v0
	v_mov_b32_e32 v16, v0
	v_mov_b32_e32 v17, v0
	v_mov_b32_e32 v18, v0
	v_mov_b32_e32 v19, v0
	v_mov_b32_e32 v20, v0
	v_mov_b32_e32 v21, v0
	v_mov_b32_e32 v22, v0
	v_mov_b32_e32 v23, v0
	v_mov_b32_e32 v24, v0
	v_mov_b32_e32 v25, v0
	v_mov_b32_e32 v26, v0
	v_mov_b32_e32 v27, v0
	v_mov_b32_e32 v28, v0
	v_mov_b32_e32 v29, v0
	v_mov_b32_e32 v30, v0
	v_mov_b32_e32 v31, v0
	v_mov_b32_e32 v32, v0
	v_mov_b32_e32 v33, v0
	v_mov_b32_e32 v34, v0
	v_mov_b32_e32 v35, v0
	v_mov_b32_e32 v36, v0
	v_mov_b32_e32 v37, v0
	v_mov_b32_e32 v38, v0
	v_mov_b32_e32 v39, v0
	s_waitcnt vmcnt(48)
; __device__ __forceinline__ void gemm_mainloop256(const bh* __restrict__ A, long lda, const bh* __restrict__ B, long ldb, int K,
;                                                  char* lds, f32x4 (&acc)[8][4]) {
;     ...
;   for (int i = 0; i < 4; ++i) { *reinterpret_cast<bf16x8*>(lds + swo + i * 8192) = ra[i]; *reinterpret_cast<bf16x8*>(lds + T_BYTES + swo + i * 8192) = rb[i]; }
; template <int OMODE>
; __device__ __forceinline__ void gemm_phase256(const bh* __restrict__ A, long lda, const bh* __restrict__ Bt, long ldb, int M, int ncols, int K,
;                                               void* Cp, long ldc, char* lds) {
;     ...
; #pragma unroll
;     for (int m = 0; m < 8; ++m)
; #pragma unroll
;       for (int n = 0; n < 4; ++n) acc[m][n] = f32x4{0.f, 0.f, 0.f, 0.f};
	v_mov_b32_e32 v40, v0
	v_mov_b32_e32 v41, v0
	v_mov_b32_e32 v42, v0
	v_mov_b32_e32 v43, v0
	v_mov_b32_e32 v44, v0
	v_mov_b32_e32 v45, v0
	v_mov_b32_e32 v46, v0
	v_mov_b32_e32 v47, v0
	v_mov_b32_e32 v48, v0
	v_mov_b32_e32 v49, v0
	v_mov_b32_e32 v50, v0
	v_mov_b32_e32 v51, v0
	v_mov_b32_e32 v52, v0
	v_mov_b32_e32 v53, v0
	v_mov_b32_e32 v54, v0
	v_mov_b32_e32 v55, v0
	v_mov_b32_e32 v56, v0
	v_mov_b32_e32 v57, v0
	v_mov_b32_e32 v58, v0
	v_mov_b32_e32 v59, v0
	v_mov_b32_e32 v60, v0
	v_mov_b32_e32 v61, v0
	v_mov_b32_e32 v62, v0
	v_mov_b32_e32 v63, v0
	v_mov_b32_e32 v72, v0
	v_mov_b32_e32 v73, v0
	v_mov_b32_e32 v74, v0
	v_mov_b32_e32 v75, v0
	v_mov_b32_e32 v84, v0
	v_mov_b32_e32 v85, v0
	v_mov_b32_e32 v86, v0
	v_mov_b32_e32 v87, v0
	v_mov_b32_e32 v88, v0
	v_mov_b32_e32 v89, v0
	v_mov_b32_e32 v90, v0
	v_mov_b32_e32 v91, v0
	v_mov_b32_e32 v100, v0
	v_mov_b32_e32 v101, v0
	v_mov_b32_e32 v102, v0
	v_mov_b32_e32 v103, v0
	v_mov_b32_e32 v112, v0
	v_mov_b32_e32 v113, v0
	v_mov_b32_e32 v114, v0
	v_mov_b32_e32 v115, v0
	v_mov_b32_e32 v116, v0
	v_mov_b32_e32 v117, v0
	v_mov_b32_e32 v118, v0
	v_mov_b32_e32 v119, v0
	v_mov_b32_e32 v120, v0
	v_mov_b32_e32 v121, v0
	v_mov_b32_e32 v122, v0
	v_mov_b32_e32 v123, v0
	v_mov_b32_e32 v124, v0
	v_mov_b32_e32 v125, v0
	v_mov_b32_e32 v126, v0
	v_mov_b32_e32 v127, v0
	s_waitcnt vmcnt(15)
	ds_write_b128 v170, v[128:131]
	s_waitcnt vmcnt(13)
	ds_write_b128 v170, v[132:135] offset:8192
	s_waitcnt vmcnt(11)
	ds_write_b128 v170, v[136:139] offset:16384
	s_waitcnt vmcnt(9)
	ds_write_b128 v170, v[140:143] offset:24576
	ds_write_b128 v170, v[144:147] offset:32768
	ds_write_b128 v170, v[148:151] offset:40960
	ds_write_b128 v170, v[152:155] offset:49152
	s_waitcnt vmcnt(8)
	ds_write_b128 v170, v[156:159] offset:57344
	v_mov_b32_e32 v128, v0
	v_mov_b32_e32 v129, v0
	v_mov_b32_e32 v130, v0
	v_mov_b32_e32 v131, v0
	v_mov_b32_e32 v132, v0
	v_mov_b32_e32 v133, v0
	v_mov_b32_e32 v134, v0
	v_mov_b32_e32 v135, v0
	v_mov_b32_e32 v136, v0
	v_mov_b32_e32 v137, v0
	v_mov_b32_e32 v138, v0
	v_mov_b32_e32 v139, v0
	v_mov_b32_e32 v140, v0
	v_mov_b32_e32 v141, v0
	v_mov_b32_e32 v142, v0
	v_mov_b32_e32 v143, v0
	v_mov_b32_e32 v144, v0
	v_mov_b32_e32 v145, v0
	v_mov_b32_e32 v146, v0
	v_mov_b32_e32 v147, v0
	v_mov_b32_e32 v148, v0
	v_mov_b32_e32 v149, v0
	v_mov_b32_e32 v150, v0
	v_mov_b32_e32 v151, v0
	v_mov_b32_e32 v152, v0
	v_mov_b32_e32 v153, v0
	v_mov_b32_e32 v154, v0
	v_mov_b32_e32 v155, v0
	v_mov_b32_e32 v156, v0
	v_mov_b32_e32 v157, v0
	v_mov_b32_e32 v158, v0
	v_mov_b32_e32 v159, v0
	s_waitcnt lgkmcnt(0)
	s_barrier
	s_branch .LBB0_1121

; __device__ __forceinline__ int tidx() { int t = threadIdx.x; asm volatile("" : "+v"(t)); return t; }
; __device__ __forceinline__ void gemm_mainloop256(const bh* __restrict__ A, long lda, const bh* __restrict__ B, long ldb, int K,
;                                                  char* lds, f32x4 (&acc)[8][4]) {
;   constexpr int T_BYTES = 256 * 128, STAGE = 2 * T_BYTES;
;   const int tid = tidx(), lane = tid & 63, wid = tid >> 6, wr = wid >> 2, wc = wid & 3, fr = lane & 15, fq = lane >> 4;
;   const int srow = tid >> 3, sch = tid & 7;
;   const bh* Ap = A + (long)srow * lda + sch * 8;
;   const bh* Bp = B + (long)srow * ldb + sch * 8;
;   const int swo = srow * 128 + ((sch ^ (srow & 7)) << 4);
;   bf16x8 ra[4], rb[4];
;   const int nk = K >> 6;
; #pragma unroll
;   for (int i = 0; i < 4; ++i) { ra[i] = *reinterpret_cast<const bf16x8*>(Ap + (long)(64 * i) * lda); rb[i] = *reinterpret_cast<const bf16x8*>(Bp + (long)(64 * i) * ldb); }
; #pragma unroll
;   for (int i = 0; i < 4; ++i) { *reinterpret_cast<bf16x8*>(lds + swo + i * 8192) = ra[i]; *reinterpret_cast<bf16x8*>(lds + T_BYTES + swo + i * 8192) = rb[i]; }
;   __syncthreads();
; template <int OMODE>
; __device__ __forceinline__ void gemm_phase256(const bh* __restrict__ A, long lda, const bh* __restrict__ Bt, long ldb, int M, int ncols, int K,
;                                               void* Cp, long ldc, char* lds) {
;   const int tm_n = M >> 8, tn_n = ncols >> 8;
;   const int tid = tidx(), lane = tid & 63, wid = tid >> 6, wr = wid >> 2, wc = wid & 3, fr = lane & 15, fq = lane >> 4;
;   for (int tile = blockIdx.x; tile < tm_n * tn_n; tile += gridDim.x) {
;     const int tn = tile / tm_n, tm = tile - tn * tm_n;
;     f32x4 acc[8][4];
; #pragma unroll
;     for (int m = 0; m < 8; ++m)
; #pragma unroll
;       for (int n = 0; n < 4; ++n) acc[m][n] = f32x4{0.f, 0.f, 0.f, 0.f};
;     gemm_mainloop256(A + (long)tm * 256 * lda, lda, Bt + (long)tn * 256 * ldb, ldb, K, lds, acc);
.LBB0_1216:
	s_ashr_i32 s0, s8, 31
	s_lshr_b32 s0, s0, 26
	s_add_i32 s0, s8, s0
	s_and_b32 s11, s0, 0xffffffc0
	s_sub_i32 s10, s8, s11
	s_ashr_i32 s9, s0, 6
	s_mul_i32 s0, s10, 0x160000
	s_mul_hi_i32 s1, s10, 0x160000
	s_add_u32 s0, s70, s0
	s_addc_u32 s1, s71, s1
	s_mul_i32 s2, s9, 0x160000
	s_mul_hi_i32 s3, s9, 0x160000
	s_add_u32 s2, s4, s2
	v_mov_b32_e32 v8, v188
	s_addc_u32 s3, s5, s3
	v_mov_b64_e32 v[0:1], s[0:1]
	v_lshlrev_b32_e32 v2, 4, v8
	v_ashrrev_i32_e32 v9, 3, v8
	s_movk_i32 s13, 0x1600
	v_and_b32_e32 v176, 0x70, v2
	v_mov_b64_e32 v[2:3], s[2:3]
	v_mad_i64_i32 v[0:1], s[0:1], v9, s13, v[0:1]
	v_mad_i64_i32 v[2:3], s[0:1], v9, s13, v[2:3]
	v_lshl_add_u64 v[0:1], v[0:1], 0, v[176:177]
	s_mov_b32 s0, 0x58000
	v_add_co_u32_e32 v4, vcc, s0, v0
	v_lshl_add_u64 v[2:3], v[2:3], 0, v[176:177]
	s_nop 0
	v_addc_co_u32_e32 v5, vcc, 0, v1, vcc
	v_add_co_u32_e32 v6, vcc, s0, v2
	s_mov_b32 s0, 0xb0000
	s_nop 0
	v_addc_co_u32_e32 v7, vcc, 0, v3, vcc
	global_load_dwordx4 v[128:131], v[0:1], off
	global_load_dwordx4 v[144:147], v[2:3], off
	global_load_dwordx4 v[132:135], v[4:5], off
	global_load_dwordx4 v[148:151], v[6:7], off
	v_add_co_u32_e32 v4, vcc, s0, v0
	s_mov_b32 s12, 0
	s_nop 0
	v_addc_co_u32_e32 v5, vcc, 0, v1, vcc
	v_add_co_u32_e32 v6, vcc, s0, v2
	s_mov_b32 s0, 0x108000
	s_nop 0
	v_addc_co_u32_e32 v7, vcc, 0, v3, vcc
	v_add_co_u32_e32 v0, vcc, s0, v0
	global_load_dwordx4 v[136:139], v[4:5], off
	global_load_dwordx4 v[152:155], v[6:7], off
	v_addc_co_u32_e32 v1, vcc, 0, v1, vcc
	global_load_dwordx4 v[140:143], v[0:1], off
	v_add_co_u32_e32 v0, vcc, s0, v2
	v_bfe_u32 v2, v8, 4, 2
	s_nop 0
	v_addc_co_u32_e32 v1, vcc, 0, v3, vcc
	global_load_dwordx4 v[156:159], v[0:1], off
	v_lshrrev_b32_e32 v0, 4, v8
	v_and_b32_e32 v1, 15, v8
	v_lshrrev_b32_e32 v3, 1, v8
	v_lshlrev_b32_e32 v4, 7, v8
	v_and_b32_e32 v5, 7, v8
	s_mov_b32 s0, 0x1ffff80
	v_and_or_b32 v3, v3, s0, v1
	v_and_b32_e32 v166, 0x6780, v4
	v_bitop3_b32 v4, v0, v5, 3 bitop3:0x6c
	v_bitop3_b32 v2, v2, v5, 4 bitop3:0x36
	v_mad_i64_i32 v[0:1], s[0:1], v9, s13, 0
	v_xor_b32_e32 v6, v9, v8
	v_lshlrev_b32_e32 v167, 7, v3
	v_lshlrev_b32_e32 v169, 4, v2
	v_mad_i64_i32 v[2:3], s[0:1], s8, v202, v[0:1]
	v_lshlrev_b32_e32 v7, 7, v9
	v_lshlrev_b32_e32 v6, 4, v6
	s_movk_i32 s0, 0x70
	v_lshlrev_b32_e32 v168, 4, v4
	v_and_or_b32 v4, v6, s0, v7
	s_mul_hi_i32 s0, s11, 0x160000
	v_lshlrev_b32_e32 v5, 4, v5
	v_add_u32_e32 v170, 32, v4
	v_mov_b32_e32 v4, s0
	v_mad_i64_i32 v[0:1], s[0:1], s9, v202, v[0:1]
	v_or_b32_e32 v2, v2, v5
	s_mul_i32 s11, s11, 0x160000
	v_readlane_b32 s0, v253, 55
	v_subrev_co_u32_e32 v2, vcc, s11, v2
	v_or_b32_e32 v0, v0, v5
	v_readlane_b32 s1, v253, 56
	v_subb_co_u32_e32 v3, vcc, v3, v4, vcc
	s_nop 0
	v_lshl_add_u64 v[162:163], s[0:1], 0, v[0:1]
	v_mov_b32_e32 v0, 0
	v_lshl_add_u64 v[160:161], s[28:29], 0, v[2:3]
	s_mov_b64 s[0:1], 0
	s_mov_b32 s11, 0
	v_lshl_add_u64 v[112:113], v[160:161], 0, s[0:1]
	v_add_co_u32_e32 v76, vcc, 0x12770000, v112
	v_lshl_add_u64 v[114:115], v[162:163], 0, s[0:1]
	s_nop 0
	v_addc_co_u32_e32 v77, vcc, 0, v113, vcc
	v_add_co_u32_e32 v80, vcc, 0x2638000, v114
	s_nop 1
	v_addc_co_u32_e32 v81, vcc, 0, v115, vcc
	v_add_co_u32_e32 v88, vcc, 0x127c8000, v112
	global_load_dwordx4 v[76:79], v[76:77], off offset:128
	s_nop 0
	global_load_dwordx4 v[80:83], v[80:81], off offset:128
	v_addc_co_u32_e32 v89, vcc, 0, v113, vcc
	v_add_co_u32_e32 v92, vcc, 0x2690000, v114
	s_nop 1
	v_addc_co_u32_e32 v93, vcc, 0, v115, vcc
	v_add_co_u32_e32 v100, vcc, 0x12820000, v112
	global_load_dwordx4 v[88:91], v[88:89], off offset:128
	s_nop 0
	global_load_dwordx4 v[92:95], v[92:93], off offset:128
	v_addc_co_u32_e32 v101, vcc, 0, v113, vcc
	v_add_co_u32_e32 v104, vcc, 0x26e8000, v114
	s_nop 1
	v_addc_co_u32_e32 v105, vcc, 0, v115, vcc
	v_add_co_u32_e32 v112, vcc, 0x12878000, v112
	global_load_dwordx4 v[100:103], v[100:101], off offset:128
	s_nop 0
	global_load_dwordx4 v[104:107], v[104:105], off offset:128
	v_addc_co_u32_e32 v113, vcc, 0, v113, vcc
	v_add_co_u32_e32 v120, vcc, 0x2740000, v114
	s_nop 1
	v_addc_co_u32_e32 v121, vcc, 0, v115, vcc
	global_load_dwordx4 v[112:115], v[112:113], off offset:128
	s_nop 0
	global_load_dwordx4 v[120:123], v[120:121], off offset:128
	v_mov_b32_e32 v1, v0
	v_mov_b32_e32 v2, v0
	v_mov_b32_e32 v3, v0
	v_mov_b32_e32 v4, v0
	v_mov_b32_e32 v5, v0
	v_mov_b32_e32 v6, v0
	v_mov_b32_e32 v7, v0
	v_mov_b32_e32 v8, v0
	v_mov_b32_e32 v9, v0
	v_mov_b32_e32 v10, v0
	v_mov_b32_e32 v11, v0
	v_mov_b32_e32 v12, v0
	v_mov_b32_e32 v13, v0
	v_mov_b32_e32 v14, v0
	v_mov_b32_e32 v15, v0
	s_waitcnt vmcnt(26)
; __device__ __forceinline__ void gemm_mainloop256(const bh* __restrict__ A, long lda, const bh* __restrict__ B, long ldb, int K,
;                                                  char* lds, f32x4 (&acc)[8][4]) {
;     ...
;   for (int i = 0; i < 4; ++i) { *reinterpret_cast<bf16x8*>(lds + swo + i * 8192) = ra[i]; *reinterpret_cast<bf16x8*>(lds + T_BYTES + swo + i * 8192) = rb[i]; }
; template <int OMODE>
; __device__ __forceinline__ void gemm_phase256(const bh* __restrict__ A, long lda, const bh* __restrict__ Bt, long ldb, int M, int ncols, int K,
;                                               void* Cp, long ldc, char* lds) {
;     ...
; #pragma unroll
;     for (int m = 0; m < 8; ++m)
; #pragma unroll
;       for (int n = 0; n < 4; ++n) acc[m][n] = f32x4{0.f, 0.f, 0.f, 0.f};
	v_mov_b32_e32 v16, v0
	v_mov_b32_e32 v17, v0
	v_mov_b32_e32 v18, v0
	v_mov_b32_e32 v19, v0
	v_mov_b32_e32 v20, v0
	v_mov_b32_e32 v21, v0
	v_mov_b32_e32 v22, v0
	v_mov_b32_e32 v23, v0
	s_waitcnt vmcnt(25)
	v_mov_b32_e32 v24, v0
	v_mov_b32_e32 v25, v0
	v_mov_b32_e32 v26, v0
	v_mov_b32_e32 v27, v0
	v_mov_b32_e32 v28, v0
	v_mov_b32_e32 v29, v0
	v_mov_b32_e32 v30, v0
	v_mov_b32_e32 v31, v0
	s_waitcnt vmcnt(24)
	v_mov_b32_e32 v32, v0
	v_mov_b32_e32 v33, v0
	v_mov_b32_e32 v34, v0
	v_mov_b32_e32 v35, v0
	v_mov_b32_e32 v36, v0
	v_mov_b32_e32 v37, v0
	v_mov_b32_e32 v38, v0
	v_mov_b32_e32 v39, v0
	v_mov_b32_e32 v40, v0
	v_mov_b32_e32 v41, v0
	v_mov_b32_e32 v42, v0
	v_mov_b32_e32 v43, v0
	v_mov_b32_e32 v44, v0
	v_mov_b32_e32 v45, v0
	v_mov_b32_e32 v46, v0
	v_mov_b32_e32 v47, v0
	v_mov_b32_e32 v48, v0
	v_mov_b32_e32 v49, v0
	v_mov_b32_e32 v50, v0
	v_mov_b32_e32 v51, v0
	v_mov_b32_e32 v52, v0
	v_mov_b32_e32 v53, v0
	v_mov_b32_e32 v54, v0
	v_mov_b32_e32 v55, v0
	v_mov_b32_e32 v56, v0
	v_mov_b32_e32 v57, v0
	v_mov_b32_e32 v58, v0
	v_mov_b32_e32 v59, v0
	v_mov_b32_e32 v60, v0
	v_mov_b32_e32 v61, v0
	v_mov_b32_e32 v62, v0
	v_mov_b32_e32 v63, v0
	v_mov_b32_e32 v64, v0
	v_mov_b32_e32 v65, v0
	v_mov_b32_e32 v66, v0
	v_mov_b32_e32 v67, v0
	v_mov_b32_e32 v68, v0
	v_mov_b32_e32 v69, v0
	v_mov_b32_e32 v70, v0
	v_mov_b32_e32 v71, v0
	v_mov_b32_e32 v72, v0
	v_mov_b32_e32 v73, v0
	v_mov_b32_e32 v74, v0
	v_mov_b32_e32 v75, v0
	v_mov_b32_e32 v84, v0
	v_mov_b32_e32 v85, v0
	v_mov_b32_e32 v86, v0
	v_mov_b32_e32 v87, v0
	v_mov_b32_e32 v96, v0
	v_mov_b32_e32 v97, v0
	v_mov_b32_e32 v98, v0
	v_mov_b32_e32 v99, v0
	v_mov_b32_e32 v108, v0
	v_mov_b32_e32 v109, v0
	v_mov_b32_e32 v110, v0
	v_mov_b32_e32 v111, v0
	v_mov_b32_e32 v116, v0
	v_mov_b32_e32 v117, v0
	v_mov_b32_e32 v118, v0
	v_mov_b32_e32 v119, v0
	v_mov_b32_e32 v124, v0
	v_mov_b32_e32 v125, v0
	v_mov_b32_e32 v126, v0
	v_mov_b32_e32 v127, v0
	s_waitcnt vmcnt(15)
	ds_write_b128 v170, v[128:131]
	s_waitcnt vmcnt(13)
	ds_write_b128 v170, v[132:135] offset:8192
	s_waitcnt vmcnt(11)
	ds_write_b128 v170, v[136:139] offset:16384
	s_waitcnt vmcnt(9)
	ds_write_b128 v170, v[140:143] offset:24576
	ds_write_b128 v170, v[144:147] offset:32768
	ds_write_b128 v170, v[148:151] offset:40960
	ds_write_b128 v170, v[152:155] offset:49152
	s_waitcnt vmcnt(8)
	ds_write_b128 v170, v[156:159] offset:57344
	v_mov_b32_e32 v128, v0
	v_mov_b32_e32 v129, v0
	v_mov_b32_e32 v130, v0
	v_mov_b32_e32 v131, v0
	v_mov_b32_e32 v132, v0
	v_mov_b32_e32 v133, v0
	v_mov_b32_e32 v134, v0
	v_mov_b32_e32 v135, v0
	v_mov_b32_e32 v136, v0
	v_mov_b32_e32 v137, v0
	v_mov_b32_e32 v138, v0
	v_mov_b32_e32 v139, v0
	v_mov_b32_e32 v140, v0
	v_mov_b32_e32 v141, v0
	v_mov_b32_e32 v142, v0
	v_mov_b32_e32 v143, v0
	v_mov_b32_e32 v144, v0
	v_mov_b32_e32 v145, v0
	v_mov_b32_e32 v146, v0
	v_mov_b32_e32 v147, v0
	v_mov_b32_e32 v148, v0
	v_mov_b32_e32 v149, v0
	v_mov_b32_e32 v150, v0
	v_mov_b32_e32 v151, v0
	v_mov_b32_e32 v152, v0
	v_mov_b32_e32 v153, v0
	v_mov_b32_e32 v154, v0
	v_mov_b32_e32 v155, v0
	v_mov_b32_e32 v156, v0
	v_mov_b32_e32 v157, v0
	v_mov_b32_e32 v158, v0
	v_mov_b32_e32 v159, v0
	s_waitcnt lgkmcnt(0)
	s_barrier
	s_branch .LBB0_1218
